# P1/P7: 6 of 8 epilogue stores deferred behind the next unit's first DMA groups; peel extended to a full 4-segment body with re-derived waits
# baseline (speedup 1.0000x reference)
; __device__ __forceinline__ unsigned cvt_pk_bf16(float lo, float hi) { unsigned r; asm volatile("v_cvt_pk_bf16_f32 %0, %1, %2" : "=v"(r) : "v"(lo), "v"(hi)); return r; }
;     __device__ __forceinline__ void operator()(Acc& acc, const Unit& u, int wr, int wc, int fr, int fq) const {
;     ...
;                 u32x4 w; w.x = cvt_pk_bf16(o[0][0], o[0][1]); w.y = cvt_pk_bf16(o[0][2], o[0][3]); w.z = cvt_pk_bf16(o[1][0], o[1][1]); w.w = cvt_pk_bf16(o[1][2], o[1][3]);
;                 *(u32x4*)(O + (size_t)row * DFF + col0) = w;
.LBB0_606:
	s_ashr_i32 s15, s14, 31
	s_lshl_b64 s[16:17], s[14:15], 19
	s_add_u32 s16, s29, s16
	s_addc_u32 s17, s30, s17
	s_and_b64 s[18:19], s[2:3], exec
	s_cselect_b32 s15, s17, s23
	s_cselect_b32 s48, s16, s22
	s_ashr_i32 s13, s12, 31
	s_lshl_b64 s[18:19], s[12:13], 19
	s_add_u32 s18, s31, s18
	s_addc_u32 s19, s33, s19
	s_and_b64 s[26:27], s[2:3], exec
	s_cselect_b32 s13, s19, s25
	s_cselect_b32 s49, s18, s24
	s_add_u32 s22, s22, 0x40080
	s_addc_u32 s23, s23, 0
	s_add_u32 s50, s24, 0x100
	v_mov_b32_e32 v0, 0
	s_addc_u32 s51, s25, 0
	s_mov_b32 s52, -2
	s_add_u32 s24, s22, 0xfffc0080
	s_addc_u32 s25, s23, -1
	s_cmp_eq_u32 s52, 12
	s_cselect_b32 s27, s15, s25
	s_cselect_b32 s26, s48, s24
	s_cselect_b32 s25, s13, s51
	s_cselect_b32 s24, s49, s50
	v_lshl_add_u64 v[218:219], s[22:23], 0, v[136:137]
	s_add_i32 m0, s21, 0xc000
	s_nop 0
	global_load_lds_dwordx4 v[218:219], off
	v_lshl_add_u64 v[218:219], s[22:23], 0, v[138:139]
	s_add_i32 m0, s21, 0xe000
	s_nop 0
	global_load_lds_dwordx4 v[218:219], off
	s_cmp_eq_u32 s101, 1
	s_cbranch_scc0 .Ldst_607_a
	v_add_u32_e32 v255, 0x2c000, v254
	global_store_dwordx4 v255, v[228:231], s[64:65]
	v_add_u32_e32 v244, 0x42000, v254
	global_store_dwordx4 v244, v[232:235], s[64:65]
.Ldst_607_a:
	s_cmp_eq_u32 s101, 1
	s_cbranch_scc1 .Lpk607_r1
	s_waitcnt vmcnt(8)
	s_branch .Lpk607_j1
.Lpk607_r1:
	s_waitcnt vmcnt(12)
.Lpk607_j1:
	s_waitcnt lgkmcnt(0)
	s_setprio 1
	s_barrier
	v_mfma_f32_16x16x32_bf16 v[124:127], v[154:157], v[186:189], 0
	v_mfma_f32_16x16x32_bf16 v[116:119], v[162:165], v[186:189], 0
	v_mfma_f32_16x16x32_bf16 v[108:111], v[154:157], v[194:197], 0
	v_mfma_f32_16x16x32_bf16 v[100:103], v[162:165], v[194:197], 0
	v_mfma_f32_16x16x32_bf16 v[92:95], v[154:157], v[202:205], 0
	v_mfma_f32_16x16x32_bf16 v[84:87], v[162:165], v[202:205], 0
	v_mfma_f32_16x16x32_bf16 v[76:79], v[154:157], v[210:213], 0
	v_mfma_f32_16x16x32_bf16 v[68:71], v[162:165], v[210:213], 0
	v_mfma_f32_16x16x32_bf16 v[124:127], v[158:161], v[190:193], v[124:127]
	v_mfma_f32_16x16x32_bf16 v[116:119], v[166:169], v[190:193], v[116:119]
	v_mfma_f32_16x16x32_bf16 v[108:111], v[158:161], v[198:201], v[108:111]
	v_mfma_f32_16x16x32_bf16 v[100:103], v[166:169], v[198:201], v[100:103]
	v_mfma_f32_16x16x32_bf16 v[92:95], v[158:161], v[206:209], v[92:95]
	v_mfma_f32_16x16x32_bf16 v[84:87], v[166:169], v[206:209], v[84:87]
	v_mfma_f32_16x16x32_bf16 v[76:79], v[158:161], v[214:217], v[76:79]
	v_mfma_f32_16x16x32_bf16 v[68:71], v[166:169], v[214:217], v[68:71]
	s_setprio 0
	s_setprio 1
	v_mfma_f32_16x16x32_bf16 v[120:123], v[170:173], v[186:189], 0
	v_mfma_f32_16x16x32_bf16 v[112:115], v[178:181], v[186:189], 0
	v_mfma_f32_16x16x32_bf16 v[104:107], v[170:173], v[194:197], 0
	v_mfma_f32_16x16x32_bf16 v[96:99], v[178:181], v[194:197], 0
	v_mfma_f32_16x16x32_bf16 v[88:91], v[170:173], v[202:205], 0
	v_mfma_f32_16x16x32_bf16 v[80:83], v[178:181], v[202:205], 0
	v_mfma_f32_16x16x32_bf16 v[72:75], v[170:173], v[210:213], 0
	v_mfma_f32_16x16x32_bf16 v[64:67], v[178:181], v[210:213], 0
	v_mfma_f32_16x16x32_bf16 v[120:123], v[174:177], v[190:193], v[120:123]
	v_mfma_f32_16x16x32_bf16 v[112:115], v[182:185], v[190:193], v[112:115]
	v_mfma_f32_16x16x32_bf16 v[104:107], v[174:177], v[198:201], v[104:107]
	v_mfma_f32_16x16x32_bf16 v[96:99], v[182:185], v[198:201], v[96:99]
	v_mfma_f32_16x16x32_bf16 v[88:91], v[174:177], v[206:209], v[88:91]
	v_mfma_f32_16x16x32_bf16 v[80:83], v[182:185], v[206:209], v[80:83]
	v_mfma_f32_16x16x32_bf16 v[72:75], v[174:177], v[214:217], v[72:75]
	v_mfma_f32_16x16x32_bf16 v[64:67], v[182:185], v[214:217], v[64:67]
	s_barrier
	s_setprio 0
	s_add_i32 s53, s40, s28
	v_lshl_add_u64 v[218:219], s[24:25], 0, v[132:133]
	s_mov_b32 m0, s53
	ds_read_b128 v[186:189], v150 offset:16384
	ds_read_b128 v[190:193], v150 offset:17408
	global_load_lds_dwordx4 v[218:219], off
	s_add_i32 m0, s53, 0x2000
	s_add_u32 s66, s24, 0x40000
	v_lshl_add_u64 v[220:221], s[24:25], 0, v[128:129]
	s_addc_u32 s67, s25, 0
	s_add_i32 s53, s41, s28
	ds_read_b128 v[194:197], v150 offset:18432
	ds_read_b128 v[198:201], v150 offset:19456
	global_load_lds_dwordx4 v[220:221], off
	v_lshl_add_u64 v[222:223], s[66:67], 0, v[132:133]
	s_mov_b32 m0, s53
	v_lshl_add_u64 v[224:225], s[26:27], 0, v[130:131]
	ds_read_b128 v[202:205], v150 offset:20480
	global_load_lds_dwordx4 v[222:223], off
	v_lshl_add_u64 v[222:223], s[66:67], 0, v[128:129]
	s_add_i32 m0, s53, 0x2000
	ds_read_b128 v[206:209], v150 offset:21504
	global_load_lds_dwordx4 v[222:223], off
	v_lshl_add_u64 v[222:223], s[26:27], 0, v[134:135]
	s_mov_b32 m0, s21
	ds_read_b128 v[210:213], v150 offset:22528
	global_load_lds_dwordx4 v[222:223], off
	s_mov_b32 m0, s35
	ds_read_b128 v[214:217], v150 offset:23552
	global_load_lds_dwordx4 v[224:225], off
	s_cmp_eq_u32 s101, 1
	s_cbranch_scc0 .Ldst_607_b
	v_add_u32_e32 v255, 0xb0000, v254
	global_store_dwordx4 v255, v[236:239], s[64:65]
	v_add_u32_e32 v244, 0xc6000, v254
	global_store_dwordx4 v244, v[240:243], s[64:65]

.Lpk607_j2:
	s_waitcnt lgkmcnt(0)
	s_setprio 1
	s_barrier
	v_mfma_f32_16x16x32_bf16 v[60:63], v[154:157], v[186:189], 0
	v_mfma_f32_16x16x32_bf16 v[52:55], v[162:165], v[186:189], 0
	v_mfma_f32_16x16x32_bf16 v[44:47], v[154:157], v[194:197], 0
	v_mfma_f32_16x16x32_bf16 v[36:39], v[162:165], v[194:197], 0
	v_mfma_f32_16x16x32_bf16 v[28:31], v[154:157], v[202:205], 0
	v_mfma_f32_16x16x32_bf16 v[20:23], v[162:165], v[202:205], 0
	v_mfma_f32_16x16x32_bf16 v[12:15], v[154:157], v[210:213], 0
	v_mfma_f32_16x16x32_bf16 v[4:7], v[162:165], v[210:213], 0
	v_mfma_f32_16x16x32_bf16 v[60:63], v[158:161], v[190:193], v[60:63]
	v_mfma_f32_16x16x32_bf16 v[52:55], v[166:169], v[190:193], v[52:55]
	v_mfma_f32_16x16x32_bf16 v[44:47], v[158:161], v[198:201], v[44:47]
	v_mfma_f32_16x16x32_bf16 v[36:39], v[166:169], v[198:201], v[36:39]
	v_mfma_f32_16x16x32_bf16 v[28:31], v[158:161], v[206:209], v[28:31]
	v_mfma_f32_16x16x32_bf16 v[20:23], v[166:169], v[206:209], v[20:23]
	v_mfma_f32_16x16x32_bf16 v[12:15], v[158:161], v[214:217], v[12:15]
	v_mfma_f32_16x16x32_bf16 v[4:7], v[166:169], v[214:217], v[4:7]
	s_setprio 0
	s_setprio 1
	v_mfma_f32_16x16x32_bf16 v[56:59], v[170:173], v[186:189], 0
	v_mfma_f32_16x16x32_bf16 v[48:51], v[178:181], v[186:189], 0
	v_mfma_f32_16x16x32_bf16 v[40:43], v[170:173], v[194:197], 0
	v_mfma_f32_16x16x32_bf16 v[32:35], v[178:181], v[194:197], 0
	v_mfma_f32_16x16x32_bf16 v[24:27], v[170:173], v[202:205], 0
	v_mfma_f32_16x16x32_bf16 v[16:19], v[178:181], v[202:205], 0
	v_mfma_f32_16x16x32_bf16 v[8:11], v[170:173], v[210:213], 0
	v_mfma_f32_16x16x32_bf16 v[0:3], v[178:181], v[210:213], 0
	v_mfma_f32_16x16x32_bf16 v[56:59], v[174:177], v[190:193], v[56:59]
	v_mfma_f32_16x16x32_bf16 v[48:51], v[182:185], v[190:193], v[48:51]
	v_mfma_f32_16x16x32_bf16 v[40:43], v[174:177], v[198:201], v[40:43]
	v_mfma_f32_16x16x32_bf16 v[32:35], v[182:185], v[198:201], v[32:35]
	v_mfma_f32_16x16x32_bf16 v[24:27], v[174:177], v[206:209], v[24:27]
	v_mfma_f32_16x16x32_bf16 v[16:19], v[182:185], v[206:209], v[16:19]
	v_mfma_f32_16x16x32_bf16 v[8:11], v[174:177], v[214:217], v[8:11]
	v_mfma_f32_16x16x32_bf16 v[0:3], v[182:185], v[214:217], v[0:3]
	s_barrier
	s_setprio 0
	s_cmp_eq_u32 s101, 1
	s_cbranch_scc0 .Ldst_607_c
	v_add_u32_e32 v255, 0xdc000, v254
	global_store_dwordx4 v255, v[246:249], s[64:65]
	v_add_u32_e32 v244, 0xf2000, v254
	global_store_dwordx4 v244, v[250:253], s[64:65]
.Ldst_607_c:
	s_add_i32 s53, 0, 0x18000
	v_add_u32_e32 v151, s53, v145
	s_add_i32 s54, 0, 0x1c000
	ds_read_b128 v[154:157], v151
	ds_read_b128 v[158:161], v151 offset:1024
	ds_read_b128 v[162:165], v151 offset:2048
	ds_read_b128 v[166:169], v151 offset:3072
	v_add_u32_e32 v151, s54, v145
	ds_read_b128 v[170:173], v151
	ds_read_b128 v[174:177], v151 offset:1024
	ds_read_b128 v[178:181], v151 offset:2048
	ds_read_b128 v[182:185], v151 offset:3072
	s_add_u32 s26, s26, 0x40000
	s_addc_u32 s27, s27, 0
	s_mov_b32 m0, s36
	v_lshl_add_u64 v[226:227], s[26:27], 0, v[134:135]
	ds_read_b128 v[186:189], v150 offset:32768
	ds_read_b128 v[190:193], v150 offset:33792
	ds_read_b128 v[194:197], v150 offset:34816
	ds_read_b128 v[198:201], v150 offset:35840
	ds_read_b128 v[202:205], v150 offset:36864
	ds_read_b128 v[206:209], v150 offset:37888
	ds_read_b128 v[210:213], v150 offset:38912
	ds_read_b128 v[214:217], v150 offset:39936
	global_load_lds_dwordx4 v[226:227], off
	v_lshl_add_u64 v[226:227], s[26:27], 0, v[130:131]
	s_mov_b32 m0, s37
	s_nop 0
	global_load_lds_dwordx4 v[226:227], off
	s_cmp_eq_u32 s101, 1
	s_cbranch_scc1 .Lpk607_w3_r
	s_waitcnt vmcnt(8)
	s_branch .Lpk607_w3_j

.Lpk607_w3_j:
	s_waitcnt lgkmcnt(0)
	s_setprio 1
	s_barrier
	v_mfma_f32_16x16x32_bf16 v[124:127], v[154:157], v[186:189], v[124:127]
	v_mfma_f32_16x16x32_bf16 v[116:119], v[162:165], v[186:189], v[116:119]
	v_mfma_f32_16x16x32_bf16 v[108:111], v[154:157], v[194:197], v[108:111]
	v_mfma_f32_16x16x32_bf16 v[100:103], v[162:165], v[194:197], v[100:103]
	v_mfma_f32_16x16x32_bf16 v[92:95], v[154:157], v[202:205], v[92:95]
	v_mfma_f32_16x16x32_bf16 v[84:87], v[162:165], v[202:205], v[84:87]
	v_mfma_f32_16x16x32_bf16 v[76:79], v[154:157], v[210:213], v[76:79]
	v_mfma_f32_16x16x32_bf16 v[68:71], v[162:165], v[210:213], v[68:71]
	v_mfma_f32_16x16x32_bf16 v[124:127], v[158:161], v[190:193], v[124:127]
	v_mfma_f32_16x16x32_bf16 v[116:119], v[166:169], v[190:193], v[116:119]
	v_mfma_f32_16x16x32_bf16 v[108:111], v[158:161], v[198:201], v[108:111]
	v_mfma_f32_16x16x32_bf16 v[100:103], v[166:169], v[198:201], v[100:103]
	v_mfma_f32_16x16x32_bf16 v[92:95], v[158:161], v[206:209], v[92:95]
	v_mfma_f32_16x16x32_bf16 v[84:87], v[166:169], v[206:209], v[84:87]
	v_mfma_f32_16x16x32_bf16 v[76:79], v[158:161], v[214:217], v[76:79]
	v_mfma_f32_16x16x32_bf16 v[68:71], v[166:169], v[214:217], v[68:71]
	s_setprio 0
	s_setprio 1
	v_mfma_f32_16x16x32_bf16 v[120:123], v[170:173], v[186:189], v[120:123]
	v_mfma_f32_16x16x32_bf16 v[112:115], v[178:181], v[186:189], v[112:115]
	v_mfma_f32_16x16x32_bf16 v[104:107], v[170:173], v[194:197], v[104:107]
	v_mfma_f32_16x16x32_bf16 v[96:99], v[178:181], v[194:197], v[96:99]
	v_mfma_f32_16x16x32_bf16 v[88:91], v[170:173], v[202:205], v[88:91]
	v_mfma_f32_16x16x32_bf16 v[80:83], v[178:181], v[202:205], v[80:83]
	v_mfma_f32_16x16x32_bf16 v[72:75], v[170:173], v[210:213], v[72:75]
	v_mfma_f32_16x16x32_bf16 v[64:67], v[178:181], v[210:213], v[64:67]
	v_mfma_f32_16x16x32_bf16 v[120:123], v[174:177], v[190:193], v[120:123]
	v_mfma_f32_16x16x32_bf16 v[112:115], v[182:185], v[190:193], v[112:115]
	v_mfma_f32_16x16x32_bf16 v[104:107], v[174:177], v[198:201], v[104:107]
	v_mfma_f32_16x16x32_bf16 v[96:99], v[182:185], v[198:201], v[96:99]
	v_mfma_f32_16x16x32_bf16 v[88:91], v[174:177], v[206:209], v[88:91]
	v_mfma_f32_16x16x32_bf16 v[80:83], v[182:185], v[206:209], v[80:83]
	v_mfma_f32_16x16x32_bf16 v[72:75], v[174:177], v[214:217], v[72:75]
	v_mfma_f32_16x16x32_bf16 v[64:67], v[182:185], v[214:217], v[64:67]
	s_barrier
	s_setprio 0
	s_add_i32 s26, s53, s28
	v_lshl_add_u64 v[218:219], v[218:219], 0, s[8:9]
	s_mov_b32 m0, s26
	ds_read_b128 v[186:189], v150 offset:49152
	ds_read_b128 v[190:193], v150 offset:50176
	global_load_lds_dwordx4 v[218:219], off
	s_add_i32 m0, s26, 0x2000
	s_add_u32 s24, s24, 0x40080
	v_lshl_add_u64 v[218:219], v[220:221], 0, s[8:9]
	s_addc_u32 s25, s25, 0
	s_add_i32 s26, s54, s28
	ds_read_b128 v[194:197], v150 offset:51200
	ds_read_b128 v[198:201], v150 offset:52224
	global_load_lds_dwordx4 v[218:219], off
	v_lshl_add_u64 v[218:219], s[24:25], 0, v[132:133]
	s_mov_b32 m0, s26
	ds_read_b128 v[202:205], v150 offset:53248
	global_load_lds_dwordx4 v[218:219], off
	v_lshl_add_u64 v[218:219], s[24:25], 0, v[128:129]
	s_add_i32 m0, s26, 0x2000
	ds_read_b128 v[206:209], v150 offset:54272
	global_load_lds_dwordx4 v[218:219], off
	v_lshl_add_u64 v[218:219], v[222:223], 0, s[8:9]
	s_mov_b32 m0, s38
	ds_read_b128 v[210:213], v150 offset:55296
	global_load_lds_dwordx4 v[218:219], off
	v_lshl_add_u64 v[218:219], v[224:225], 0, s[8:9]
	s_mov_b32 m0, s39
	ds_read_b128 v[214:217], v150 offset:56320
	global_load_lds_dwordx4 v[218:219], off
	s_cmp_eq_u32 s101, 1
	s_cbranch_scc1 .Lpk607_w4_r
	s_waitcnt vmcnt(8)
	s_branch .Lpk607_w4_j

.Lpk607_w4_j:
	s_mov_b32 s101, 0
	s_waitcnt lgkmcnt(0)
	s_setprio 1
	s_barrier
	v_mfma_f32_16x16x32_bf16 v[60:63], v[154:157], v[186:189], v[60:63]
	v_mfma_f32_16x16x32_bf16 v[52:55], v[162:165], v[186:189], v[52:55]
	v_mfma_f32_16x16x32_bf16 v[44:47], v[154:157], v[194:197], v[44:47]
	v_mfma_f32_16x16x32_bf16 v[36:39], v[162:165], v[194:197], v[36:39]
	v_mfma_f32_16x16x32_bf16 v[28:31], v[154:157], v[202:205], v[28:31]
	v_mfma_f32_16x16x32_bf16 v[20:23], v[162:165], v[202:205], v[20:23]
	v_mfma_f32_16x16x32_bf16 v[12:15], v[154:157], v[210:213], v[12:15]
	v_mfma_f32_16x16x32_bf16 v[4:7], v[162:165], v[210:213], v[4:7]
	v_mfma_f32_16x16x32_bf16 v[60:63], v[158:161], v[190:193], v[60:63]
	v_mfma_f32_16x16x32_bf16 v[52:55], v[166:169], v[190:193], v[52:55]
	v_mfma_f32_16x16x32_bf16 v[44:47], v[158:161], v[198:201], v[44:47]
	v_mfma_f32_16x16x32_bf16 v[36:39], v[166:169], v[198:201], v[36:39]
	v_mfma_f32_16x16x32_bf16 v[28:31], v[158:161], v[206:209], v[28:31]
	v_mfma_f32_16x16x32_bf16 v[20:23], v[166:169], v[206:209], v[20:23]
	v_mfma_f32_16x16x32_bf16 v[12:15], v[158:161], v[214:217], v[12:15]
	v_mfma_f32_16x16x32_bf16 v[4:7], v[166:169], v[214:217], v[4:7]
	s_setprio 0
	s_setprio 1
	v_mfma_f32_16x16x32_bf16 v[56:59], v[170:173], v[186:189], v[56:59]
	v_mfma_f32_16x16x32_bf16 v[48:51], v[178:181], v[186:189], v[48:51]
	v_mfma_f32_16x16x32_bf16 v[40:43], v[170:173], v[194:197], v[40:43]
	v_mfma_f32_16x16x32_bf16 v[32:35], v[178:181], v[194:197], v[32:35]
	v_mfma_f32_16x16x32_bf16 v[24:27], v[170:173], v[202:205], v[24:27]
	v_mfma_f32_16x16x32_bf16 v[16:19], v[178:181], v[202:205], v[16:19]
	v_mfma_f32_16x16x32_bf16 v[8:11], v[170:173], v[210:213], v[8:11]
	v_mfma_f32_16x16x32_bf16 v[0:3], v[178:181], v[210:213], v[0:3]
	v_mfma_f32_16x16x32_bf16 v[56:59], v[174:177], v[190:193], v[56:59]
	v_mfma_f32_16x16x32_bf16 v[48:51], v[182:185], v[190:193], v[48:51]
	v_mfma_f32_16x16x32_bf16 v[40:43], v[174:177], v[198:201], v[40:43]
	v_mfma_f32_16x16x32_bf16 v[32:35], v[182:185], v[198:201], v[32:35]
	v_mfma_f32_16x16x32_bf16 v[24:27], v[174:177], v[206:209], v[24:27]
	v_mfma_f32_16x16x32_bf16 v[16:19], v[182:185], v[206:209], v[16:19]
	v_mfma_f32_16x16x32_bf16 v[8:11], v[174:177], v[214:217], v[8:11]
	v_mfma_f32_16x16x32_bf16 v[0:3], v[182:185], v[214:217], v[0:3]
	s_barrier
	s_setprio 0
	s_branch .Lpk607_tail

; __device__ __forceinline__ unsigned cvt_pk_bf16(float lo, float hi) { unsigned r; asm volatile("v_cvt_pk_bf16_f32 %0, %1, %2" : "=v"(r) : "v"(lo), "v"(hi)); return r; }
; #define PG8_BAR __builtin_amdgcn_s_barrier()
;     __device__ __forceinline__ void operator()(Acc& acc, const Unit& u, int wr, int wc, int fr, int fq) const {
;         const int row0 = u.pm * BM + wr * 64 + fr, col0 = u.pn * 128 + wc * 32 + 8 * fq;
; #pragma unroll
;         for (int ai = 0; ai < 2; ++ai)
; #pragma unroll
;             for (int m = 0; m < 4; ++m) {
;                 const int row = row0 + ai * HALF + m * 16;
;                 const float r = rs[u.idx * BM + wr * 64 + fr + ai * HALF + m * 16];
;                 const float c1 = -r * 1.4426950408889634f, r2 = r * r;
;                 f32x4 o[2];
; #pragma unroll
;                 for (int n = 0; n < 2; ++n) {
;                     const f32x4 g = acc[ai][0][m][n], up = acc[ai][1][m][n];
;                     const f32x4 t = g * c1; f32x4 e;
; #pragma unroll
;                     for (int i = 0; i < 4; ++i) e[i] = __builtin_amdgcn_exp2f(t[i]);
;                     const f32x4 d = e + 1.0f; f32x4 q;
; #pragma unroll
;                     for (int i = 0; i < 4; ++i) q[i] = __builtin_amdgcn_rcpf(d[i]);
;                     o[n] = (g * up) * (q * r2);
;                 }
;                 u32x4 w; w.x = cvt_pk_bf16(o[0][0], o[0][1]); w.y = cvt_pk_bf16(o[0][2], o[0][3]); w.z = cvt_pk_bf16(o[1][0], o[1][1]); w.w = cvt_pk_bf16(o[1][2], o[1][3]);
;                 *(u32x4*)(O + (size_t)row * DFF + col0) = w;
; template <class Epi, class Sched, bool ALIGN_EPI>
; __device__ __forceinline__ void gemm_phase(LAS unsigned char* lds, const Gemm g, const Sched& S, const Epi& E) {
;     ...
;             for (int t = 0; t < nt; t += 2) PG8_KBODY(t);
;         }
;         if constexpr (ALIGN_EPI) { if (wr == 0) PG8_BAR; }
.Lpk607_tail:
	s_add_i32 s52, s52, 2
	s_add_u32 s22, s22, 0x100
	s_addc_u32 s23, s23, 0
	s_add_u32 s50, s50, 0x100
	s_addc_u32 s51, s51, 0
	s_cmp_gt_u32 s52, 13
	s_cbranch_scc0 .LBB0_607
	s_and_b64 vcc, exec, s[10:11]
	s_cbranch_vccz .LBB0_610
	s_barrier
.LBB0_610:
	v_lshl_add_u32 v154, s45, 10, v146
	ds_read_b32 v200, v154
	ds_read_b32 v201, v154 offset:64
	ds_read_b32 v202, v154 offset:128
	ds_read_b32 v203, v154 offset:192
	ds_read_b32 v204, v154 offset:512
	ds_read_b32 v205, v154 offset:576
	ds_read_b32 v206, v154 offset:640
	ds_read_b32 v207, v154 offset:704
	v_lshl_or_b32 v156, s47, 7, v147
	v_lshl_add_u32 v151, s20, 8, v144
	v_lshlrev_b32_e32 v156, 1, v156
	v_mov_b32_e32 v198, 1.0
	v_mad_u32_u24 v155, v151, s42, v156
	s_waitcnt lgkmcnt(0)
	v_mul_f32_e32 v158, 0xbfb8aa3b, v200
	v_mul_f32_e32 v160, v200, v200
	v_pk_mul_f32 v[162:163], v[124:125], v[158:159] op_sel_hi:[1,0]
	v_pk_mul_f32 v[164:165], v[126:127], v[158:159] op_sel_hi:[1,0]
	v_pk_mul_f32 v[166:167], v[116:117], v[158:159] op_sel_hi:[1,0]
	v_pk_mul_f32 v[168:169], v[118:119], v[158:159] op_sel_hi:[1,0]
	v_exp_f32_e32 v162, v162
	v_exp_f32_e32 v163, v163
	v_pk_mul_f32 v[120:121], v[124:125], v[120:121]
	v_exp_f32_e32 v164, v164
	v_exp_f32_e32 v165, v165
	v_pk_mul_f32 v[122:123], v[126:127], v[122:123]
	v_exp_f32_e32 v166, v166
	v_exp_f32_e32 v167, v167
	v_pk_mul_f32 v[112:113], v[116:117], v[112:113]
	v_exp_f32_e32 v168, v168
	v_exp_f32_e32 v169, v169
	v_pk_mul_f32 v[114:115], v[118:119], v[114:115]
	v_pk_add_f32 v[162:163], v[162:163], v[198:199] op_sel_hi:[1,0]
	v_pk_add_f32 v[164:165], v[164:165], v[198:199] op_sel_hi:[1,0]
	v_pk_add_f32 v[166:167], v[166:167], v[198:199] op_sel_hi:[1,0]
	v_pk_add_f32 v[168:169], v[168:169], v[198:199] op_sel_hi:[1,0]
	v_rcp_f32_e32 v162, v162
	v_rcp_f32_e32 v163, v163
	v_rcp_f32_e32 v164, v164
	v_rcp_f32_e32 v165, v165
	v_rcp_f32_e32 v166, v166
	v_rcp_f32_e32 v167, v167
	v_rcp_f32_e32 v168, v168
	v_rcp_f32_e32 v169, v169
	v_pk_mul_f32 v[162:163], v[160:161], v[162:163] op_sel_hi:[0,1]
	v_pk_mul_f32 v[164:165], v[160:161], v[164:165] op_sel_hi:[0,1]
	v_pk_mul_f32 v[166:167], v[160:161], v[166:167] op_sel_hi:[0,1]
	v_pk_mul_f32 v[168:169], v[160:161], v[168:169] op_sel_hi:[0,1]
	v_pk_mul_f32 v[120:121], v[120:121], v[162:163]
	v_pk_mul_f32 v[122:123], v[122:123], v[164:165]
	v_pk_mul_f32 v[112:113], v[112:113], v[166:167]
	v_pk_mul_f32 v[114:115], v[114:115], v[168:169]
	v_cvt_pk_bf16_f32 v170, v120, v121
	v_cvt_pk_bf16_f32 v171, v122, v123
	v_cvt_pk_bf16_f32 v172, v112, v113
	v_cvt_pk_bf16_f32 v173, v114, v115
	global_store_dwordx4 v155, v[170:173], s[64:65]
	v_mul_f32_e32 v158, 0xbfb8aa3b, v201
	v_mul_f32_e32 v160, v201, v201
	v_pk_mul_f32 v[162:163], v[108:109], v[158:159] op_sel_hi:[1,0]
	v_pk_mul_f32 v[164:165], v[110:111], v[158:159] op_sel_hi:[1,0]
	v_pk_mul_f32 v[166:167], v[100:101], v[158:159] op_sel_hi:[1,0]
	v_pk_mul_f32 v[168:169], v[102:103], v[158:159] op_sel_hi:[1,0]
	v_exp_f32_e32 v162, v162
	v_exp_f32_e32 v163, v163
	v_pk_mul_f32 v[104:105], v[108:109], v[104:105]
	v_exp_f32_e32 v164, v164
	v_exp_f32_e32 v165, v165
	v_pk_mul_f32 v[106:107], v[110:111], v[106:107]
	v_exp_f32_e32 v166, v166
	v_exp_f32_e32 v167, v167
	v_pk_mul_f32 v[96:97], v[100:101], v[96:97]
	v_exp_f32_e32 v168, v168
	v_exp_f32_e32 v169, v169
	v_pk_mul_f32 v[98:99], v[102:103], v[98:99]
	v_pk_add_f32 v[162:163], v[162:163], v[198:199] op_sel_hi:[1,0]
	v_pk_add_f32 v[164:165], v[164:165], v[198:199] op_sel_hi:[1,0]
	v_pk_add_f32 v[166:167], v[166:167], v[198:199] op_sel_hi:[1,0]
	v_pk_add_f32 v[168:169], v[168:169], v[198:199] op_sel_hi:[1,0]
	v_rcp_f32_e32 v162, v162
	v_rcp_f32_e32 v163, v163
	v_rcp_f32_e32 v164, v164
	v_rcp_f32_e32 v165, v165
	v_rcp_f32_e32 v166, v166
	v_rcp_f32_e32 v167, v167
	v_rcp_f32_e32 v168, v168
	v_rcp_f32_e32 v169, v169
	v_pk_mul_f32 v[162:163], v[160:161], v[162:163] op_sel_hi:[0,1]
	v_pk_mul_f32 v[164:165], v[160:161], v[164:165] op_sel_hi:[0,1]
	v_pk_mul_f32 v[166:167], v[160:161], v[166:167] op_sel_hi:[0,1]
	v_pk_mul_f32 v[168:169], v[160:161], v[168:169] op_sel_hi:[0,1]
	v_pk_mul_f32 v[104:105], v[104:105], v[162:163]
	v_pk_mul_f32 v[106:107], v[106:107], v[164:165]
	v_pk_mul_f32 v[96:97], v[96:97], v[166:167]
	v_pk_mul_f32 v[98:99], v[98:99], v[168:169]
	v_cvt_pk_bf16_f32 v176, v104, v105
	v_cvt_pk_bf16_f32 v177, v106, v107
	v_cvt_pk_bf16_f32 v178, v96, v97
	v_cvt_pk_bf16_f32 v179, v98, v99
	v_add_u32_e32 v175, 0x16000, v155
	global_store_dwordx4 v175, v[176:179], s[64:65]
	v_mul_f32_e32 v158, 0xbfb8aa3b, v202
	v_mul_f32_e32 v160, v202, v202
	v_pk_mul_f32 v[162:163], v[92:93], v[158:159] op_sel_hi:[1,0]
	v_pk_mul_f32 v[164:165], v[94:95], v[158:159] op_sel_hi:[1,0]
	v_pk_mul_f32 v[166:167], v[84:85], v[158:159] op_sel_hi:[1,0]
	v_pk_mul_f32 v[168:169], v[86:87], v[158:159] op_sel_hi:[1,0]
	v_exp_f32_e32 v162, v162
	v_exp_f32_e32 v163, v163
	v_pk_mul_f32 v[88:89], v[92:93], v[88:89]
	v_exp_f32_e32 v164, v164
	v_exp_f32_e32 v165, v165
	v_pk_mul_f32 v[90:91], v[94:95], v[90:91]
	v_exp_f32_e32 v166, v166
	v_exp_f32_e32 v167, v167
	v_pk_mul_f32 v[80:81], v[84:85], v[80:81]
	v_exp_f32_e32 v168, v168
	v_exp_f32_e32 v169, v169
	v_pk_mul_f32 v[82:83], v[86:87], v[82:83]
	v_pk_add_f32 v[162:163], v[162:163], v[198:199] op_sel_hi:[1,0]
	v_pk_add_f32 v[164:165], v[164:165], v[198:199] op_sel_hi:[1,0]
	v_pk_add_f32 v[166:167], v[166:167], v[198:199] op_sel_hi:[1,0]
	v_pk_add_f32 v[168:169], v[168:169], v[198:199] op_sel_hi:[1,0]
	v_rcp_f32_e32 v162, v162
	v_rcp_f32_e32 v163, v163
	v_rcp_f32_e32 v164, v164
	v_rcp_f32_e32 v165, v165
	v_rcp_f32_e32 v166, v166
	v_rcp_f32_e32 v167, v167
	v_rcp_f32_e32 v168, v168
	v_rcp_f32_e32 v169, v169
; __device__ __forceinline__ unsigned cvt_pk_bf16(float lo, float hi) { unsigned r; asm volatile("v_cvt_pk_bf16_f32 %0, %1, %2" : "=v"(r) : "v"(lo), "v"(hi)); return r; }
;     __device__ __forceinline__ void operator()(Acc& acc, const Unit& u, int wr, int wc, int fr, int fq) const {
;     ...
;             for (int m = 0; m < 4; ++m) {
;                 const int row = row0 + ai * HALF + m * 16;
;                 const float r = rs[u.idx * BM + wr * 64 + fr + ai * HALF + m * 16];
;                 const float c1 = -r * 1.4426950408889634f, r2 = r * r;
;                 f32x4 o[2];
; #pragma unroll
;                 for (int n = 0; n < 2; ++n) {
;                     const f32x4 g = acc[ai][0][m][n], up = acc[ai][1][m][n];
;                     const f32x4 t = g * c1; f32x4 e;
; #pragma unroll
;                     for (int i = 0; i < 4; ++i) e[i] = __builtin_amdgcn_exp2f(t[i]);
;                     const f32x4 d = e + 1.0f; f32x4 q;
; #pragma unroll
;                     for (int i = 0; i < 4; ++i) q[i] = __builtin_amdgcn_rcpf(d[i]);
;                     o[n] = (g * up) * (q * r2);
;                 }
;                 u32x4 w; w.x = cvt_pk_bf16(o[0][0], o[0][1]); w.y = cvt_pk_bf16(o[0][2], o[0][3]); w.z = cvt_pk_bf16(o[1][0], o[1][1]); w.w = cvt_pk_bf16(o[1][2], o[1][3]);
;                 *(u32x4*)(O + (size_t)row * DFF + col0) = w;
	v_pk_mul_f32 v[162:163], v[160:161], v[162:163] op_sel_hi:[0,1]
	v_pk_mul_f32 v[164:165], v[160:161], v[164:165] op_sel_hi:[0,1]
	v_pk_mul_f32 v[166:167], v[160:161], v[166:167] op_sel_hi:[0,1]
	v_pk_mul_f32 v[168:169], v[160:161], v[168:169] op_sel_hi:[0,1]
	v_pk_mul_f32 v[88:89], v[88:89], v[162:163]
	v_pk_mul_f32 v[90:91], v[90:91], v[164:165]
	v_pk_mul_f32 v[80:81], v[80:81], v[166:167]
	v_pk_mul_f32 v[82:83], v[82:83], v[168:169]
	v_cvt_pk_bf16_f32 v228, v88, v89
	v_cvt_pk_bf16_f32 v229, v90, v91
	v_cvt_pk_bf16_f32 v230, v80, v81
	v_cvt_pk_bf16_f32 v231, v82, v83
	v_mul_f32_e32 v158, 0xbfb8aa3b, v203
	v_mul_f32_e32 v160, v203, v203
	v_pk_mul_f32 v[162:163], v[76:77], v[158:159] op_sel_hi:[1,0]
	v_pk_mul_f32 v[164:165], v[78:79], v[158:159] op_sel_hi:[1,0]
	v_pk_mul_f32 v[166:167], v[68:69], v[158:159] op_sel_hi:[1,0]
	v_pk_mul_f32 v[168:169], v[70:71], v[158:159] op_sel_hi:[1,0]
	v_exp_f32_e32 v162, v162
	v_exp_f32_e32 v163, v163
	v_pk_mul_f32 v[72:73], v[76:77], v[72:73]
	v_exp_f32_e32 v164, v164
	v_exp_f32_e32 v165, v165
	v_pk_mul_f32 v[74:75], v[78:79], v[74:75]
	v_exp_f32_e32 v166, v166
	v_exp_f32_e32 v167, v167
	v_pk_mul_f32 v[64:65], v[68:69], v[64:65]
	v_exp_f32_e32 v168, v168
	v_exp_f32_e32 v169, v169
	v_pk_mul_f32 v[66:67], v[70:71], v[66:67]
	v_pk_add_f32 v[162:163], v[162:163], v[198:199] op_sel_hi:[1,0]
	v_pk_add_f32 v[164:165], v[164:165], v[198:199] op_sel_hi:[1,0]
	v_pk_add_f32 v[166:167], v[166:167], v[198:199] op_sel_hi:[1,0]
	v_pk_add_f32 v[168:169], v[168:169], v[198:199] op_sel_hi:[1,0]
	v_rcp_f32_e32 v162, v162
	v_rcp_f32_e32 v163, v163
	v_rcp_f32_e32 v164, v164
	v_rcp_f32_e32 v165, v165
	v_rcp_f32_e32 v166, v166
	v_rcp_f32_e32 v167, v167
	v_rcp_f32_e32 v168, v168
	v_rcp_f32_e32 v169, v169
	v_pk_mul_f32 v[162:163], v[160:161], v[162:163] op_sel_hi:[0,1]
	v_pk_mul_f32 v[164:165], v[160:161], v[164:165] op_sel_hi:[0,1]
	v_pk_mul_f32 v[166:167], v[160:161], v[166:167] op_sel_hi:[0,1]
	v_pk_mul_f32 v[168:169], v[160:161], v[168:169] op_sel_hi:[0,1]
	v_pk_mul_f32 v[72:73], v[72:73], v[162:163]
	v_pk_mul_f32 v[74:75], v[74:75], v[164:165]
	v_pk_mul_f32 v[64:65], v[64:65], v[166:167]
	v_pk_mul_f32 v[66:67], v[66:67], v[168:169]
	v_cvt_pk_bf16_f32 v232, v72, v73
	v_cvt_pk_bf16_f32 v233, v74, v75
	v_cvt_pk_bf16_f32 v234, v64, v65
	v_cvt_pk_bf16_f32 v235, v66, v67
	v_mul_f32_e32 v158, 0xbfb8aa3b, v204
	v_mul_f32_e32 v160, v204, v204
	v_pk_mul_f32 v[162:163], v[60:61], v[158:159] op_sel_hi:[1,0]
	v_pk_mul_f32 v[164:165], v[62:63], v[158:159] op_sel_hi:[1,0]
	v_pk_mul_f32 v[166:167], v[52:53], v[158:159] op_sel_hi:[1,0]
	v_pk_mul_f32 v[168:169], v[54:55], v[158:159] op_sel_hi:[1,0]
	v_exp_f32_e32 v162, v162
	v_exp_f32_e32 v163, v163
	v_pk_mul_f32 v[56:57], v[60:61], v[56:57]
	v_exp_f32_e32 v164, v164
	v_exp_f32_e32 v165, v165
	v_pk_mul_f32 v[58:59], v[62:63], v[58:59]
	v_exp_f32_e32 v166, v166
	v_exp_f32_e32 v167, v167
	v_pk_mul_f32 v[48:49], v[52:53], v[48:49]
	v_exp_f32_e32 v168, v168
	v_exp_f32_e32 v169, v169
	v_pk_mul_f32 v[50:51], v[54:55], v[50:51]
	v_pk_add_f32 v[162:163], v[162:163], v[198:199] op_sel_hi:[1,0]
	v_pk_add_f32 v[164:165], v[164:165], v[198:199] op_sel_hi:[1,0]
	v_pk_add_f32 v[166:167], v[166:167], v[198:199] op_sel_hi:[1,0]
	v_pk_add_f32 v[168:169], v[168:169], v[198:199] op_sel_hi:[1,0]
	v_rcp_f32_e32 v162, v162
	v_rcp_f32_e32 v163, v163
	v_rcp_f32_e32 v164, v164
	v_rcp_f32_e32 v165, v165
	v_rcp_f32_e32 v166, v166
	v_rcp_f32_e32 v167, v167
	v_rcp_f32_e32 v168, v168
	v_rcp_f32_e32 v169, v169
	v_pk_mul_f32 v[162:163], v[160:161], v[162:163] op_sel_hi:[0,1]
	v_pk_mul_f32 v[164:165], v[160:161], v[164:165] op_sel_hi:[0,1]
	v_pk_mul_f32 v[166:167], v[160:161], v[166:167] op_sel_hi:[0,1]
	v_pk_mul_f32 v[168:169], v[160:161], v[168:169] op_sel_hi:[0,1]
	v_pk_mul_f32 v[56:57], v[56:57], v[162:163]
	v_pk_mul_f32 v[58:59], v[58:59], v[164:165]
	v_pk_mul_f32 v[48:49], v[48:49], v[166:167]
	v_pk_mul_f32 v[50:51], v[50:51], v[168:169]
	v_cvt_pk_bf16_f32 v236, v56, v57
	v_cvt_pk_bf16_f32 v237, v58, v59
	v_cvt_pk_bf16_f32 v238, v48, v49
	v_cvt_pk_bf16_f32 v239, v50, v51
	v_mul_f32_e32 v158, 0xbfb8aa3b, v205
	v_mul_f32_e32 v160, v205, v205
	v_pk_mul_f32 v[162:163], v[44:45], v[158:159] op_sel_hi:[1,0]
	v_pk_mul_f32 v[164:165], v[46:47], v[158:159] op_sel_hi:[1,0]
	v_pk_mul_f32 v[166:167], v[36:37], v[158:159] op_sel_hi:[1,0]
	v_pk_mul_f32 v[168:169], v[38:39], v[158:159] op_sel_hi:[1,0]
	v_exp_f32_e32 v162, v162
	v_exp_f32_e32 v163, v163
	v_pk_mul_f32 v[40:41], v[44:45], v[40:41]
	v_exp_f32_e32 v164, v164
	v_exp_f32_e32 v165, v165
	v_pk_mul_f32 v[42:43], v[46:47], v[42:43]
	v_exp_f32_e32 v166, v166
	v_exp_f32_e32 v167, v167
	v_pk_mul_f32 v[32:33], v[36:37], v[32:33]
	v_exp_f32_e32 v168, v168
	v_exp_f32_e32 v169, v169
	v_pk_mul_f32 v[34:35], v[38:39], v[34:35]
	v_pk_add_f32 v[162:163], v[162:163], v[198:199] op_sel_hi:[1,0]
	v_pk_add_f32 v[164:165], v[164:165], v[198:199] op_sel_hi:[1,0]
	v_pk_add_f32 v[166:167], v[166:167], v[198:199] op_sel_hi:[1,0]
	v_pk_add_f32 v[168:169], v[168:169], v[198:199] op_sel_hi:[1,0]
; __device__ __forceinline__ unsigned cvt_pk_bf16(float lo, float hi) { unsigned r; asm volatile("v_cvt_pk_bf16_f32 %0, %1, %2" : "=v"(r) : "v"(lo), "v"(hi)); return r; }
; #define PG8_BAR __builtin_amdgcn_s_barrier()
;     __device__ __forceinline__ void operator()(Acc& acc, const Unit& u, int wr, int wc, int fr, int fq) const {
;     ...
;                     const f32x4 g = acc[ai][0][m][n], up = acc[ai][1][m][n];
;                     const f32x4 t = g * c1; f32x4 e;
; #pragma unroll
;                     for (int i = 0; i < 4; ++i) e[i] = __builtin_amdgcn_exp2f(t[i]);
;                     const f32x4 d = e + 1.0f; f32x4 q;
; #pragma unroll
;                     for (int i = 0; i < 4; ++i) q[i] = __builtin_amdgcn_rcpf(d[i]);
;                     o[n] = (g * up) * (q * r2);
;                 }
;                 u32x4 w; w.x = cvt_pk_bf16(o[0][0], o[0][1]); w.y = cvt_pk_bf16(o[0][2], o[0][3]); w.z = cvt_pk_bf16(o[1][0], o[1][1]); w.w = cvt_pk_bf16(o[1][2], o[1][3]);
;                 *(u32x4*)(O + (size_t)row * DFF + col0) = w;
; template <class Epi, class Sched, bool ALIGN_EPI>
; __device__ __forceinline__ void gemm_phase(LAS unsigned char* lds, const Gemm g, const Sched& S, const Epi& E) {
;     ...
;         E(acc, cur, wr, wc, fr, fq);
;         if (!has_next) break;
; #pragma unroll
;         for (int a = 0; a < 2; ++a)
; #pragma unroll
;             for (int b = 0; b < 2; ++b)
; #pragma unroll
;                 for (int m = 0; m < 4; ++m)
; #pragma unroll
;                     for (int n = 0; n < 2; ++n) acc[a][b][m][n] = (f32x4){0.f, 0.f, 0.f, 0.f};
;         cur = nxt; cA = nA; cB = nB; ++ui;
;         if constexpr (ALIGN_EPI) { if (wr == 1) PG8_BAR; }
	v_rcp_f32_e32 v162, v162
	v_rcp_f32_e32 v163, v163
	v_rcp_f32_e32 v164, v164
	v_rcp_f32_e32 v165, v165
	v_rcp_f32_e32 v166, v166
	v_rcp_f32_e32 v167, v167
	v_rcp_f32_e32 v168, v168
	v_rcp_f32_e32 v169, v169
	v_pk_mul_f32 v[162:163], v[160:161], v[162:163] op_sel_hi:[0,1]
	v_pk_mul_f32 v[164:165], v[160:161], v[164:165] op_sel_hi:[0,1]
	v_pk_mul_f32 v[166:167], v[160:161], v[166:167] op_sel_hi:[0,1]
	v_pk_mul_f32 v[168:169], v[160:161], v[168:169] op_sel_hi:[0,1]
	v_pk_mul_f32 v[40:41], v[40:41], v[162:163]
	v_pk_mul_f32 v[42:43], v[42:43], v[164:165]
	v_pk_mul_f32 v[32:33], v[32:33], v[166:167]
	v_pk_mul_f32 v[34:35], v[34:35], v[168:169]
	v_cvt_pk_bf16_f32 v240, v40, v41
	v_cvt_pk_bf16_f32 v241, v42, v43
	v_cvt_pk_bf16_f32 v242, v32, v33
	v_cvt_pk_bf16_f32 v243, v34, v35
	v_mul_f32_e32 v158, 0xbfb8aa3b, v206
	v_mul_f32_e32 v160, v206, v206
	v_pk_mul_f32 v[162:163], v[28:29], v[158:159] op_sel_hi:[1,0]
	v_pk_mul_f32 v[164:165], v[30:31], v[158:159] op_sel_hi:[1,0]
	v_pk_mul_f32 v[166:167], v[20:21], v[158:159] op_sel_hi:[1,0]
	v_pk_mul_f32 v[168:169], v[22:23], v[158:159] op_sel_hi:[1,0]
	v_exp_f32_e32 v162, v162
	v_exp_f32_e32 v163, v163
	v_pk_mul_f32 v[24:25], v[28:29], v[24:25]
	v_exp_f32_e32 v164, v164
	v_exp_f32_e32 v165, v165
	v_pk_mul_f32 v[26:27], v[30:31], v[26:27]
	v_exp_f32_e32 v166, v166
	v_exp_f32_e32 v167, v167
	v_pk_mul_f32 v[16:17], v[20:21], v[16:17]
	v_exp_f32_e32 v168, v168
	v_exp_f32_e32 v169, v169
	v_pk_mul_f32 v[18:19], v[22:23], v[18:19]
	v_pk_add_f32 v[162:163], v[162:163], v[198:199] op_sel_hi:[1,0]
	v_pk_add_f32 v[164:165], v[164:165], v[198:199] op_sel_hi:[1,0]
	v_pk_add_f32 v[166:167], v[166:167], v[198:199] op_sel_hi:[1,0]
	v_pk_add_f32 v[168:169], v[168:169], v[198:199] op_sel_hi:[1,0]
	v_rcp_f32_e32 v162, v162
	v_rcp_f32_e32 v163, v163
	v_rcp_f32_e32 v164, v164
	v_rcp_f32_e32 v165, v165
	v_rcp_f32_e32 v166, v166
	v_rcp_f32_e32 v167, v167
	v_rcp_f32_e32 v168, v168
	v_rcp_f32_e32 v169, v169
	v_pk_mul_f32 v[162:163], v[160:161], v[162:163] op_sel_hi:[0,1]
	v_pk_mul_f32 v[164:165], v[160:161], v[164:165] op_sel_hi:[0,1]
	v_pk_mul_f32 v[166:167], v[160:161], v[166:167] op_sel_hi:[0,1]
	v_pk_mul_f32 v[168:169], v[160:161], v[168:169] op_sel_hi:[0,1]
	v_pk_mul_f32 v[24:25], v[24:25], v[162:163]
	v_pk_mul_f32 v[26:27], v[26:27], v[164:165]
	v_pk_mul_f32 v[16:17], v[16:17], v[166:167]
	v_pk_mul_f32 v[18:19], v[18:19], v[168:169]
	v_cvt_pk_bf16_f32 v246, v24, v25
	v_cvt_pk_bf16_f32 v247, v26, v27
	v_cvt_pk_bf16_f32 v248, v16, v17
	v_cvt_pk_bf16_f32 v249, v18, v19
	v_mul_f32_e32 v158, 0xbfb8aa3b, v207
	v_mul_f32_e32 v160, v207, v207
	v_pk_mul_f32 v[162:163], v[12:13], v[158:159] op_sel_hi:[1,0]
	v_pk_mul_f32 v[164:165], v[14:15], v[158:159] op_sel_hi:[1,0]
	v_pk_mul_f32 v[166:167], v[4:5], v[158:159] op_sel_hi:[1,0]
	v_pk_mul_f32 v[168:169], v[6:7], v[158:159] op_sel_hi:[1,0]
	v_exp_f32_e32 v162, v162
	v_exp_f32_e32 v163, v163
	v_pk_mul_f32 v[8:9], v[12:13], v[8:9]
	v_exp_f32_e32 v164, v164
	v_exp_f32_e32 v165, v165
	v_pk_mul_f32 v[10:11], v[14:15], v[10:11]
	v_exp_f32_e32 v166, v166
	v_exp_f32_e32 v167, v167
	v_pk_mul_f32 v[0:1], v[4:5], v[0:1]
	v_exp_f32_e32 v168, v168
	v_exp_f32_e32 v169, v169
	v_pk_mul_f32 v[2:3], v[6:7], v[2:3]
	v_pk_add_f32 v[162:163], v[162:163], v[198:199] op_sel_hi:[1,0]
	v_pk_add_f32 v[164:165], v[164:165], v[198:199] op_sel_hi:[1,0]
	v_pk_add_f32 v[166:167], v[166:167], v[198:199] op_sel_hi:[1,0]
	v_pk_add_f32 v[168:169], v[168:169], v[198:199] op_sel_hi:[1,0]
	v_rcp_f32_e32 v162, v162
	v_rcp_f32_e32 v163, v163
	v_rcp_f32_e32 v164, v164
	v_rcp_f32_e32 v165, v165
	v_rcp_f32_e32 v166, v166
	v_rcp_f32_e32 v167, v167
	v_rcp_f32_e32 v168, v168
	v_rcp_f32_e32 v169, v169
	v_pk_mul_f32 v[162:163], v[160:161], v[162:163] op_sel_hi:[0,1]
	v_pk_mul_f32 v[164:165], v[160:161], v[164:165] op_sel_hi:[0,1]
	v_pk_mul_f32 v[166:167], v[160:161], v[166:167] op_sel_hi:[0,1]
	v_pk_mul_f32 v[168:169], v[160:161], v[168:169] op_sel_hi:[0,1]
	v_pk_mul_f32 v[8:9], v[8:9], v[162:163]
	v_pk_mul_f32 v[10:11], v[10:11], v[164:165]
	v_pk_mul_f32 v[0:1], v[0:1], v[166:167]
	v_pk_mul_f32 v[2:3], v[2:3], v[168:169]
	v_cvt_pk_bf16_f32 v250, v8, v9
	v_cvt_pk_bf16_f32 v251, v10, v11
	v_cvt_pk_bf16_f32 v252, v0, v1
	v_cvt_pk_bf16_f32 v253, v2, v3
	v_mov_b32_e32 v254, v155
	s_andn2_b64 vcc, exec, s[2:3]
	s_mov_b64 s[2:3], -1
	s_mov_b32 s101, 1
	s_cbranch_vccz .Lswg_def_607
	v_add_u32_e32 v255, 0x2c000, v254
	global_store_dwordx4 v255, v[228:231], s[64:65]
	v_add_u32_e32 v244, 0x42000, v254
	global_store_dwordx4 v244, v[232:235], s[64:65]
	v_add_u32_e32 v255, 0xb0000, v254
	global_store_dwordx4 v255, v[236:239], s[64:65]
	v_add_u32_e32 v244, 0xc6000, v254
	global_store_dwordx4 v244, v[240:243], s[64:65]
	v_add_u32_e32 v255, 0xdc000, v254
	global_store_dwordx4 v255, v[246:249], s[64:65]
	v_add_u32_e32 v244, 0xf2000, v254
	global_store_dwordx4 v244, v[250:253], s[64:65]
	s_branch .LBB0_603
.Lswg_def_607:
	s_andn2_b64 vcc, exec, s[6:7]
	s_cbranch_vccnz .LBB0_602
	s_barrier
	s_branch .LBB0_602

; template <class Epi, class Sched, bool ALIGN_EPI>
; __device__ __forceinline__ void gemm_phase(LAS unsigned char* lds, const Gemm g, const Sched& S, const Epi& E) {
;     ...
;         const bool has_next = S.next(ui + 1, nxt);
;         const char* nA = has_next ? (const char*)g.A + (size_t)nxt.pm * tstepA : cA; const char* nB = has_next ? (const char*)g.Bt + (size_t)nxt.pn * tstepB : cB;
.LBB0_1612:
	s_ashr_i32 s13, s12, 31
	s_lshl_b64 s[14:15], s[12:13], 19
	s_add_u32 s14, s27, s14
	s_addc_u32 s15, s28, s15
	s_and_b64 s[16:17], s[2:3], exec
	s_cselect_b32 s13, s15, s21
	s_cselect_b32 s45, s14, s20
	s_ashr_i32 s11, s10, 31
	s_lshl_b64 s[16:17], s[10:11], 19
	s_add_u32 s16, s29, s16
	s_addc_u32 s17, s30, s17
	s_and_b64 s[24:25], s[2:3], exec
	s_cselect_b32 s11, s17, s23
	s_cselect_b32 s46, s16, s22
	s_add_u32 s20, s20, 0x40080
	s_addc_u32 s21, s21, 0
	s_add_u32 s47, s22, 0x100
	v_mov_b32_e32 v0, 0
	s_addc_u32 s48, s23, 0
	s_mov_b32 s49, -2
	s_add_u32 s22, s20, 0xfffc0080
	s_addc_u32 s23, s21, -1
	s_cmp_eq_u32 s49, 12
	s_cselect_b32 s25, s13, s23
	s_cselect_b32 s24, s45, s22
	s_cselect_b32 s23, s11, s48
	s_cselect_b32 s22, s46, s47
	v_lshl_add_u64 v[218:219], s[20:21], 0, v[136:137]
	s_add_i32 m0, s19, 0xc000
	s_nop 0
	global_load_lds_dwordx4 v[218:219], off
	v_lshl_add_u64 v[218:219], s[20:21], 0, v[138:139]
	s_add_i32 m0, s19, 0xe000
	s_nop 0
	global_load_lds_dwordx4 v[218:219], off
	s_cmp_eq_u32 s101, 1
	s_cbranch_scc0 .Ldst_1613_a
	v_add_u32_e32 v255, 0x2c000, v254
	global_store_dwordx4 v255, v[228:231], s[64:65]
	v_add_u32_e32 v244, 0x42000, v254
	global_store_dwordx4 v244, v[232:235], s[64:65]

.Lpk1613_j1:
	s_waitcnt lgkmcnt(0)
	s_setprio 1
	s_barrier
	v_mfma_f32_16x16x32_bf16 v[124:127], v[154:157], v[186:189], 0
	v_mfma_f32_16x16x32_bf16 v[116:119], v[162:165], v[186:189], 0
	v_mfma_f32_16x16x32_bf16 v[108:111], v[154:157], v[194:197], 0
	v_mfma_f32_16x16x32_bf16 v[100:103], v[162:165], v[194:197], 0
	v_mfma_f32_16x16x32_bf16 v[92:95], v[154:157], v[202:205], 0
	v_mfma_f32_16x16x32_bf16 v[84:87], v[162:165], v[202:205], 0
	v_mfma_f32_16x16x32_bf16 v[76:79], v[154:157], v[210:213], 0
	v_mfma_f32_16x16x32_bf16 v[68:71], v[162:165], v[210:213], 0
	v_mfma_f32_16x16x32_bf16 v[124:127], v[158:161], v[190:193], v[124:127]
	v_mfma_f32_16x16x32_bf16 v[116:119], v[166:169], v[190:193], v[116:119]
	v_mfma_f32_16x16x32_bf16 v[108:111], v[158:161], v[198:201], v[108:111]
	v_mfma_f32_16x16x32_bf16 v[100:103], v[166:169], v[198:201], v[100:103]
	v_mfma_f32_16x16x32_bf16 v[92:95], v[158:161], v[206:209], v[92:95]
	v_mfma_f32_16x16x32_bf16 v[84:87], v[166:169], v[206:209], v[84:87]
	v_mfma_f32_16x16x32_bf16 v[76:79], v[158:161], v[214:217], v[76:79]
	v_mfma_f32_16x16x32_bf16 v[68:71], v[166:169], v[214:217], v[68:71]
	s_setprio 0
	s_setprio 1
	v_mfma_f32_16x16x32_bf16 v[120:123], v[170:173], v[186:189], 0
	v_mfma_f32_16x16x32_bf16 v[112:115], v[178:181], v[186:189], 0
	v_mfma_f32_16x16x32_bf16 v[104:107], v[170:173], v[194:197], 0
	v_mfma_f32_16x16x32_bf16 v[96:99], v[178:181], v[194:197], 0
	v_mfma_f32_16x16x32_bf16 v[88:91], v[170:173], v[202:205], 0
	v_mfma_f32_16x16x32_bf16 v[80:83], v[178:181], v[202:205], 0
	v_mfma_f32_16x16x32_bf16 v[72:75], v[170:173], v[210:213], 0
	v_mfma_f32_16x16x32_bf16 v[64:67], v[178:181], v[210:213], 0
	v_mfma_f32_16x16x32_bf16 v[120:123], v[174:177], v[190:193], v[120:123]
	v_mfma_f32_16x16x32_bf16 v[112:115], v[182:185], v[190:193], v[112:115]
	v_mfma_f32_16x16x32_bf16 v[104:107], v[174:177], v[198:201], v[104:107]
	v_mfma_f32_16x16x32_bf16 v[96:99], v[182:185], v[198:201], v[96:99]
	v_mfma_f32_16x16x32_bf16 v[88:91], v[174:177], v[206:209], v[88:91]
	v_mfma_f32_16x16x32_bf16 v[80:83], v[182:185], v[206:209], v[80:83]
	v_mfma_f32_16x16x32_bf16 v[72:75], v[174:177], v[214:217], v[72:75]
	v_mfma_f32_16x16x32_bf16 v[64:67], v[182:185], v[214:217], v[64:67]
	s_barrier
	s_setprio 0
	s_add_i32 s50, s38, s26
	v_lshl_add_u64 v[218:219], s[22:23], 0, v[132:133]
	s_mov_b32 m0, s50
	ds_read_b128 v[186:189], v150 offset:16384
	ds_read_b128 v[190:193], v150 offset:17408
	global_load_lds_dwordx4 v[218:219], off
	s_add_i32 m0, s50, 0x2000
	s_add_u32 s50, s22, 0x40000
	v_lshl_add_u64 v[220:221], s[22:23], 0, v[128:129]
	s_addc_u32 s51, s23, 0
	s_add_i32 s52, s39, s26
	ds_read_b128 v[194:197], v150 offset:18432
	ds_read_b128 v[198:201], v150 offset:19456
	global_load_lds_dwordx4 v[220:221], off
	v_lshl_add_u64 v[222:223], s[50:51], 0, v[132:133]
	s_mov_b32 m0, s52
	v_lshl_add_u64 v[224:225], s[24:25], 0, v[130:131]
	ds_read_b128 v[202:205], v150 offset:20480
	global_load_lds_dwordx4 v[222:223], off
	v_lshl_add_u64 v[222:223], s[50:51], 0, v[128:129]
	s_add_i32 m0, s52, 0x2000
	ds_read_b128 v[206:209], v150 offset:21504
	global_load_lds_dwordx4 v[222:223], off
	v_lshl_add_u64 v[222:223], s[24:25], 0, v[134:135]
	s_mov_b32 m0, s19
	ds_read_b128 v[210:213], v150 offset:22528
	global_load_lds_dwordx4 v[222:223], off
	s_mov_b32 m0, s33
	ds_read_b128 v[214:217], v150 offset:23552
	global_load_lds_dwordx4 v[224:225], off
	s_cmp_eq_u32 s101, 1
	s_cbranch_scc0 .Ldst_1613_b
	v_add_u32_e32 v255, 0xb0000, v254
	global_store_dwordx4 v255, v[236:239], s[64:65]
	v_add_u32_e32 v244, 0xc6000, v254
	global_store_dwordx4 v244, v[240:243], s[64:65]

.Ldst_1613_c:
	s_add_i32 s50, 0, 0x18000
	v_add_u32_e32 v151, s50, v145
	s_add_i32 s51, 0, 0x1c000
	ds_read_b128 v[154:157], v151
	ds_read_b128 v[158:161], v151 offset:1024
	ds_read_b128 v[162:165], v151 offset:2048
	ds_read_b128 v[166:169], v151 offset:3072
	v_add_u32_e32 v151, s51, v145
	ds_read_b128 v[170:173], v151
	ds_read_b128 v[174:177], v151 offset:1024
	ds_read_b128 v[178:181], v151 offset:2048
	ds_read_b128 v[182:185], v151 offset:3072
	s_add_u32 s24, s24, 0x40000
	s_addc_u32 s25, s25, 0
	s_mov_b32 m0, s34
	v_lshl_add_u64 v[226:227], s[24:25], 0, v[134:135]
	ds_read_b128 v[186:189], v150 offset:32768
	ds_read_b128 v[190:193], v150 offset:33792
	ds_read_b128 v[194:197], v150 offset:34816
	ds_read_b128 v[198:201], v150 offset:35840
	ds_read_b128 v[202:205], v150 offset:36864
	ds_read_b128 v[206:209], v150 offset:37888
	ds_read_b128 v[210:213], v150 offset:38912
	ds_read_b128 v[214:217], v150 offset:39936
	global_load_lds_dwordx4 v[226:227], off
	v_lshl_add_u64 v[226:227], s[24:25], 0, v[130:131]
	s_mov_b32 m0, s35
	s_nop 0
	global_load_lds_dwordx4 v[226:227], off
	s_cmp_eq_u32 s101, 1
	s_cbranch_scc1 .Lpk1613_w3_r
	s_waitcnt vmcnt(8)
	s_branch .Lpk1613_w3_j

.Lpk1613_w3_j:
	s_waitcnt lgkmcnt(0)
	s_setprio 1
	s_barrier
	v_mfma_f32_16x16x32_bf16 v[124:127], v[154:157], v[186:189], v[124:127]
	v_mfma_f32_16x16x32_bf16 v[116:119], v[162:165], v[186:189], v[116:119]
	v_mfma_f32_16x16x32_bf16 v[108:111], v[154:157], v[194:197], v[108:111]
	v_mfma_f32_16x16x32_bf16 v[100:103], v[162:165], v[194:197], v[100:103]
	v_mfma_f32_16x16x32_bf16 v[92:95], v[154:157], v[202:205], v[92:95]
	v_mfma_f32_16x16x32_bf16 v[84:87], v[162:165], v[202:205], v[84:87]
	v_mfma_f32_16x16x32_bf16 v[76:79], v[154:157], v[210:213], v[76:79]
	v_mfma_f32_16x16x32_bf16 v[68:71], v[162:165], v[210:213], v[68:71]
	v_mfma_f32_16x16x32_bf16 v[124:127], v[158:161], v[190:193], v[124:127]
	v_mfma_f32_16x16x32_bf16 v[116:119], v[166:169], v[190:193], v[116:119]
	v_mfma_f32_16x16x32_bf16 v[108:111], v[158:161], v[198:201], v[108:111]
	v_mfma_f32_16x16x32_bf16 v[100:103], v[166:169], v[198:201], v[100:103]
	v_mfma_f32_16x16x32_bf16 v[92:95], v[158:161], v[206:209], v[92:95]
	v_mfma_f32_16x16x32_bf16 v[84:87], v[166:169], v[206:209], v[84:87]
	v_mfma_f32_16x16x32_bf16 v[76:79], v[158:161], v[214:217], v[76:79]
	v_mfma_f32_16x16x32_bf16 v[68:71], v[166:169], v[214:217], v[68:71]
	s_setprio 0
	s_setprio 1
	v_mfma_f32_16x16x32_bf16 v[120:123], v[170:173], v[186:189], v[120:123]
	v_mfma_f32_16x16x32_bf16 v[112:115], v[178:181], v[186:189], v[112:115]
	v_mfma_f32_16x16x32_bf16 v[104:107], v[170:173], v[194:197], v[104:107]
	v_mfma_f32_16x16x32_bf16 v[96:99], v[178:181], v[194:197], v[96:99]
	v_mfma_f32_16x16x32_bf16 v[88:91], v[170:173], v[202:205], v[88:91]
	v_mfma_f32_16x16x32_bf16 v[80:83], v[178:181], v[202:205], v[80:83]
	v_mfma_f32_16x16x32_bf16 v[72:75], v[170:173], v[210:213], v[72:75]
	v_mfma_f32_16x16x32_bf16 v[64:67], v[178:181], v[210:213], v[64:67]
	v_mfma_f32_16x16x32_bf16 v[120:123], v[174:177], v[190:193], v[120:123]
	v_mfma_f32_16x16x32_bf16 v[112:115], v[182:185], v[190:193], v[112:115]
	v_mfma_f32_16x16x32_bf16 v[104:107], v[174:177], v[198:201], v[104:107]
	v_mfma_f32_16x16x32_bf16 v[96:99], v[182:185], v[198:201], v[96:99]
	v_mfma_f32_16x16x32_bf16 v[88:91], v[174:177], v[206:209], v[88:91]
	v_mfma_f32_16x16x32_bf16 v[80:83], v[182:185], v[206:209], v[80:83]
	v_mfma_f32_16x16x32_bf16 v[72:75], v[174:177], v[214:217], v[72:75]
	v_mfma_f32_16x16x32_bf16 v[64:67], v[182:185], v[214:217], v[64:67]
	s_barrier
	s_setprio 0
	s_add_i32 s24, s50, s26
	v_lshl_add_u64 v[218:219], v[218:219], 0, s[6:7]
	s_mov_b32 m0, s24
	ds_read_b128 v[186:189], v150 offset:49152
	ds_read_b128 v[190:193], v150 offset:50176
	global_load_lds_dwordx4 v[218:219], off
	s_add_i32 m0, s24, 0x2000
	s_add_u32 s22, s22, 0x40080
	v_lshl_add_u64 v[218:219], v[220:221], 0, s[6:7]
	s_addc_u32 s23, s23, 0
	s_add_i32 s24, s51, s26
	ds_read_b128 v[194:197], v150 offset:51200
	ds_read_b128 v[198:201], v150 offset:52224
	global_load_lds_dwordx4 v[218:219], off
	v_lshl_add_u64 v[218:219], s[22:23], 0, v[132:133]
	s_mov_b32 m0, s24
	ds_read_b128 v[202:205], v150 offset:53248
	global_load_lds_dwordx4 v[218:219], off
	v_lshl_add_u64 v[218:219], s[22:23], 0, v[128:129]
	s_add_i32 m0, s24, 0x2000
	ds_read_b128 v[206:209], v150 offset:54272
	global_load_lds_dwordx4 v[218:219], off
	v_lshl_add_u64 v[218:219], v[222:223], 0, s[6:7]
	s_mov_b32 m0, s36
	ds_read_b128 v[210:213], v150 offset:55296
	global_load_lds_dwordx4 v[218:219], off
	v_lshl_add_u64 v[218:219], v[224:225], 0, s[6:7]
	s_mov_b32 m0, s37
	ds_read_b128 v[214:217], v150 offset:56320
	global_load_lds_dwordx4 v[218:219], off
	s_cmp_eq_u32 s101, 1
	s_cbranch_scc1 .Lpk1613_w4_r
	s_waitcnt vmcnt(8)
	s_branch .Lpk1613_w4_j

; __device__ __forceinline__ unsigned cvt_pk_bf16(float lo, float hi) { unsigned r; asm volatile("v_cvt_pk_bf16_f32 %0, %1, %2" : "=v"(r) : "v"(lo), "v"(hi)); return r; }
; #define PG8_BAR __builtin_amdgcn_s_barrier()
;     __device__ __forceinline__ void operator()(Acc& acc, const Unit& u, int wr, int wc, int fr, int fq) const {
;         const int row0 = u.pm * BM + wr * 64 + fr, col0 = u.pn * 128 + wc * 32 + 8 * fq;
; #pragma unroll
;         for (int ai = 0; ai < 2; ++ai)
; #pragma unroll
;             for (int m = 0; m < 4; ++m) {
;                 const int row = row0 + ai * HALF + m * 16;
;                 const float r = rs[u.idx * BM + wr * 64 + fr + ai * HALF + m * 16];
;                 const float c1 = -r * 1.4426950408889634f, r2 = r * r;
;                 f32x4 o[2];
; #pragma unroll
;                 for (int n = 0; n < 2; ++n) {
;                     const f32x4 g = acc[ai][0][m][n], up = acc[ai][1][m][n];
;                     const f32x4 t = g * c1; f32x4 e;
; #pragma unroll
;                     for (int i = 0; i < 4; ++i) e[i] = __builtin_amdgcn_exp2f(t[i]);
;                     const f32x4 d = e + 1.0f; f32x4 q;
; #pragma unroll
;                     for (int i = 0; i < 4; ++i) q[i] = __builtin_amdgcn_rcpf(d[i]);
;                     o[n] = (g * up) * (q * r2);
;                 }
;                 u32x4 w; w.x = cvt_pk_bf16(o[0][0], o[0][1]); w.y = cvt_pk_bf16(o[0][2], o[0][3]); w.z = cvt_pk_bf16(o[1][0], o[1][1]); w.w = cvt_pk_bf16(o[1][2], o[1][3]);
;                 *(u32x4*)(O + (size_t)row * DFF + col0) = w;
; template <class Epi, class Sched, bool ALIGN_EPI>
; __device__ __forceinline__ void gemm_phase(LAS unsigned char* lds, const Gemm g, const Sched& S, const Epi& E) {
;     ...
;             for (int t = 0; t < nt; t += 2) PG8_KBODY(t);
;         }
;         if constexpr (ALIGN_EPI) { if (wr == 0) PG8_BAR; }
.Lpk1613_tail:
	s_add_i32 s49, s49, 2
	s_add_u32 s20, s20, 0x100
	s_addc_u32 s21, s21, 0
	s_add_u32 s47, s47, 0x100
	s_addc_u32 s48, s48, 0
	s_cmp_gt_u32 s49, 13
	s_cbranch_scc0 .LBB0_1613
	s_and_b64 vcc, exec, s[8:9]
	s_cbranch_vccz .LBB0_1616
	s_barrier
.LBB0_1616:
	v_lshl_add_u32 v154, s43, 10, v146
	ds_read_b32 v200, v154
	ds_read_b32 v201, v154 offset:64
	ds_read_b32 v202, v154 offset:128
	ds_read_b32 v203, v154 offset:192
	ds_read_b32 v204, v154 offset:512
	ds_read_b32 v205, v154 offset:576
	ds_read_b32 v206, v154 offset:640
	ds_read_b32 v207, v154 offset:704
	v_lshl_or_b32 v156, s44, 7, v147
	v_lshl_add_u32 v151, s18, 8, v144
	v_lshlrev_b32_e32 v156, 1, v156
	v_mov_b32_e32 v198, 1.0
	v_mad_u32_u24 v155, v151, s40, v156
	s_waitcnt lgkmcnt(0)
	v_mul_f32_e32 v158, 0xbfb8aa3b, v200
	v_mul_f32_e32 v160, v200, v200
	v_pk_mul_f32 v[162:163], v[124:125], v[158:159] op_sel_hi:[1,0]
	v_pk_mul_f32 v[164:165], v[126:127], v[158:159] op_sel_hi:[1,0]
	v_pk_mul_f32 v[166:167], v[116:117], v[158:159] op_sel_hi:[1,0]
	v_pk_mul_f32 v[168:169], v[118:119], v[158:159] op_sel_hi:[1,0]
	v_exp_f32_e32 v162, v162
	v_exp_f32_e32 v163, v163
	v_pk_mul_f32 v[120:121], v[124:125], v[120:121]
	v_exp_f32_e32 v164, v164
	v_exp_f32_e32 v165, v165
	v_pk_mul_f32 v[122:123], v[126:127], v[122:123]
	v_exp_f32_e32 v166, v166
	v_exp_f32_e32 v167, v167
	v_pk_mul_f32 v[112:113], v[116:117], v[112:113]
	v_exp_f32_e32 v168, v168
	v_exp_f32_e32 v169, v169
	v_pk_mul_f32 v[114:115], v[118:119], v[114:115]
	v_pk_add_f32 v[162:163], v[162:163], v[198:199] op_sel_hi:[1,0]
	v_pk_add_f32 v[164:165], v[164:165], v[198:199] op_sel_hi:[1,0]
	v_pk_add_f32 v[166:167], v[166:167], v[198:199] op_sel_hi:[1,0]
	v_pk_add_f32 v[168:169], v[168:169], v[198:199] op_sel_hi:[1,0]
	v_rcp_f32_e32 v162, v162
	v_rcp_f32_e32 v163, v163
	v_rcp_f32_e32 v164, v164
	v_rcp_f32_e32 v165, v165
	v_rcp_f32_e32 v166, v166
	v_rcp_f32_e32 v167, v167
	v_rcp_f32_e32 v168, v168
	v_rcp_f32_e32 v169, v169
	v_pk_mul_f32 v[162:163], v[160:161], v[162:163] op_sel_hi:[0,1]
	v_pk_mul_f32 v[164:165], v[160:161], v[164:165] op_sel_hi:[0,1]
	v_pk_mul_f32 v[166:167], v[160:161], v[166:167] op_sel_hi:[0,1]
	v_pk_mul_f32 v[168:169], v[160:161], v[168:169] op_sel_hi:[0,1]
	v_pk_mul_f32 v[120:121], v[120:121], v[162:163]
	v_pk_mul_f32 v[122:123], v[122:123], v[164:165]
	v_pk_mul_f32 v[112:113], v[112:113], v[166:167]
	v_pk_mul_f32 v[114:115], v[114:115], v[168:169]
	v_cvt_pk_bf16_f32 v170, v120, v121
	v_cvt_pk_bf16_f32 v171, v122, v123
	v_cvt_pk_bf16_f32 v172, v112, v113
	v_cvt_pk_bf16_f32 v173, v114, v115
	global_store_dwordx4 v155, v[170:173], s[64:65]
	v_mul_f32_e32 v158, 0xbfb8aa3b, v201
	v_mul_f32_e32 v160, v201, v201
	v_pk_mul_f32 v[162:163], v[108:109], v[158:159] op_sel_hi:[1,0]
	v_pk_mul_f32 v[164:165], v[110:111], v[158:159] op_sel_hi:[1,0]
	v_pk_mul_f32 v[166:167], v[100:101], v[158:159] op_sel_hi:[1,0]
	v_pk_mul_f32 v[168:169], v[102:103], v[158:159] op_sel_hi:[1,0]
	v_exp_f32_e32 v162, v162
	v_exp_f32_e32 v163, v163
	v_pk_mul_f32 v[104:105], v[108:109], v[104:105]
	v_exp_f32_e32 v164, v164
	v_exp_f32_e32 v165, v165
	v_pk_mul_f32 v[106:107], v[110:111], v[106:107]
	v_exp_f32_e32 v166, v166
	v_exp_f32_e32 v167, v167
	v_pk_mul_f32 v[96:97], v[100:101], v[96:97]
	v_exp_f32_e32 v168, v168
	v_exp_f32_e32 v169, v169
	v_pk_mul_f32 v[98:99], v[102:103], v[98:99]
	v_pk_add_f32 v[162:163], v[162:163], v[198:199] op_sel_hi:[1,0]
	v_pk_add_f32 v[164:165], v[164:165], v[198:199] op_sel_hi:[1,0]
	v_pk_add_f32 v[166:167], v[166:167], v[198:199] op_sel_hi:[1,0]
	v_pk_add_f32 v[168:169], v[168:169], v[198:199] op_sel_hi:[1,0]
	v_rcp_f32_e32 v162, v162
	v_rcp_f32_e32 v163, v163
	v_rcp_f32_e32 v164, v164
	v_rcp_f32_e32 v165, v165
	v_rcp_f32_e32 v166, v166
	v_rcp_f32_e32 v167, v167
	v_rcp_f32_e32 v168, v168
	v_rcp_f32_e32 v169, v169
	v_pk_mul_f32 v[162:163], v[160:161], v[162:163] op_sel_hi:[0,1]
	v_pk_mul_f32 v[164:165], v[160:161], v[164:165] op_sel_hi:[0,1]
	v_pk_mul_f32 v[166:167], v[160:161], v[166:167] op_sel_hi:[0,1]
	v_pk_mul_f32 v[168:169], v[160:161], v[168:169] op_sel_hi:[0,1]
	v_pk_mul_f32 v[104:105], v[104:105], v[162:163]
	v_pk_mul_f32 v[106:107], v[106:107], v[164:165]
	v_pk_mul_f32 v[96:97], v[96:97], v[166:167]
	v_pk_mul_f32 v[98:99], v[98:99], v[168:169]
	v_cvt_pk_bf16_f32 v176, v104, v105
	v_cvt_pk_bf16_f32 v177, v106, v107
	v_cvt_pk_bf16_f32 v178, v96, v97
	v_cvt_pk_bf16_f32 v179, v98, v99
	v_add_u32_e32 v175, 0x16000, v155
	global_store_dwordx4 v175, v[176:179], s[64:65]
	v_mul_f32_e32 v158, 0xbfb8aa3b, v202
	v_mul_f32_e32 v160, v202, v202
	v_pk_mul_f32 v[162:163], v[92:93], v[158:159] op_sel_hi:[1,0]
	v_pk_mul_f32 v[164:165], v[94:95], v[158:159] op_sel_hi:[1,0]
	v_pk_mul_f32 v[166:167], v[84:85], v[158:159] op_sel_hi:[1,0]
	v_pk_mul_f32 v[168:169], v[86:87], v[158:159] op_sel_hi:[1,0]
	v_exp_f32_e32 v162, v162
	v_exp_f32_e32 v163, v163
	v_pk_mul_f32 v[88:89], v[92:93], v[88:89]
	v_exp_f32_e32 v164, v164
	v_exp_f32_e32 v165, v165
	v_pk_mul_f32 v[90:91], v[94:95], v[90:91]
	v_exp_f32_e32 v166, v166
	v_exp_f32_e32 v167, v167
	v_pk_mul_f32 v[80:81], v[84:85], v[80:81]
	v_exp_f32_e32 v168, v168
	v_exp_f32_e32 v169, v169
	v_pk_mul_f32 v[82:83], v[86:87], v[82:83]
	v_pk_add_f32 v[162:163], v[162:163], v[198:199] op_sel_hi:[1,0]
	v_pk_add_f32 v[164:165], v[164:165], v[198:199] op_sel_hi:[1,0]
	v_pk_add_f32 v[166:167], v[166:167], v[198:199] op_sel_hi:[1,0]
	v_pk_add_f32 v[168:169], v[168:169], v[198:199] op_sel_hi:[1,0]
	v_rcp_f32_e32 v162, v162
	v_rcp_f32_e32 v163, v163
	v_rcp_f32_e32 v164, v164
	v_rcp_f32_e32 v165, v165
	v_rcp_f32_e32 v166, v166
	v_rcp_f32_e32 v167, v167
	v_rcp_f32_e32 v168, v168
	v_rcp_f32_e32 v169, v169
; __device__ __forceinline__ unsigned cvt_pk_bf16(float lo, float hi) { unsigned r; asm volatile("v_cvt_pk_bf16_f32 %0, %1, %2" : "=v"(r) : "v"(lo), "v"(hi)); return r; }
;     __device__ __forceinline__ void operator()(Acc& acc, const Unit& u, int wr, int wc, int fr, int fq) const {
;     ...
;             for (int m = 0; m < 4; ++m) {
;                 const int row = row0 + ai * HALF + m * 16;
;                 const float r = rs[u.idx * BM + wr * 64 + fr + ai * HALF + m * 16];
;                 const float c1 = -r * 1.4426950408889634f, r2 = r * r;
;                 f32x4 o[2];
; #pragma unroll
;                 for (int n = 0; n < 2; ++n) {
;                     const f32x4 g = acc[ai][0][m][n], up = acc[ai][1][m][n];
;                     const f32x4 t = g * c1; f32x4 e;
; #pragma unroll
;                     for (int i = 0; i < 4; ++i) e[i] = __builtin_amdgcn_exp2f(t[i]);
;                     const f32x4 d = e + 1.0f; f32x4 q;
; #pragma unroll
;                     for (int i = 0; i < 4; ++i) q[i] = __builtin_amdgcn_rcpf(d[i]);
;                     o[n] = (g * up) * (q * r2);
;                 }
;                 u32x4 w; w.x = cvt_pk_bf16(o[0][0], o[0][1]); w.y = cvt_pk_bf16(o[0][2], o[0][3]); w.z = cvt_pk_bf16(o[1][0], o[1][1]); w.w = cvt_pk_bf16(o[1][2], o[1][3]);
;                 *(u32x4*)(O + (size_t)row * DFF + col0) = w;
	v_pk_mul_f32 v[162:163], v[160:161], v[162:163] op_sel_hi:[0,1]
	v_pk_mul_f32 v[164:165], v[160:161], v[164:165] op_sel_hi:[0,1]
	v_pk_mul_f32 v[166:167], v[160:161], v[166:167] op_sel_hi:[0,1]
	v_pk_mul_f32 v[168:169], v[160:161], v[168:169] op_sel_hi:[0,1]
	v_pk_mul_f32 v[88:89], v[88:89], v[162:163]
	v_pk_mul_f32 v[90:91], v[90:91], v[164:165]
	v_pk_mul_f32 v[80:81], v[80:81], v[166:167]
	v_pk_mul_f32 v[82:83], v[82:83], v[168:169]
	v_cvt_pk_bf16_f32 v228, v88, v89
	v_cvt_pk_bf16_f32 v229, v90, v91
	v_cvt_pk_bf16_f32 v230, v80, v81
	v_cvt_pk_bf16_f32 v231, v82, v83
	v_mul_f32_e32 v158, 0xbfb8aa3b, v203
	v_mul_f32_e32 v160, v203, v203
	v_pk_mul_f32 v[162:163], v[76:77], v[158:159] op_sel_hi:[1,0]
	v_pk_mul_f32 v[164:165], v[78:79], v[158:159] op_sel_hi:[1,0]
	v_pk_mul_f32 v[166:167], v[68:69], v[158:159] op_sel_hi:[1,0]
	v_pk_mul_f32 v[168:169], v[70:71], v[158:159] op_sel_hi:[1,0]
	v_exp_f32_e32 v162, v162
	v_exp_f32_e32 v163, v163
	v_pk_mul_f32 v[72:73], v[76:77], v[72:73]
	v_exp_f32_e32 v164, v164
	v_exp_f32_e32 v165, v165
	v_pk_mul_f32 v[74:75], v[78:79], v[74:75]
	v_exp_f32_e32 v166, v166
	v_exp_f32_e32 v167, v167
	v_pk_mul_f32 v[64:65], v[68:69], v[64:65]
	v_exp_f32_e32 v168, v168
	v_exp_f32_e32 v169, v169
	v_pk_mul_f32 v[66:67], v[70:71], v[66:67]
	v_pk_add_f32 v[162:163], v[162:163], v[198:199] op_sel_hi:[1,0]
	v_pk_add_f32 v[164:165], v[164:165], v[198:199] op_sel_hi:[1,0]
	v_pk_add_f32 v[166:167], v[166:167], v[198:199] op_sel_hi:[1,0]
	v_pk_add_f32 v[168:169], v[168:169], v[198:199] op_sel_hi:[1,0]
	v_rcp_f32_e32 v162, v162
	v_rcp_f32_e32 v163, v163
	v_rcp_f32_e32 v164, v164
	v_rcp_f32_e32 v165, v165
	v_rcp_f32_e32 v166, v166
	v_rcp_f32_e32 v167, v167
	v_rcp_f32_e32 v168, v168
	v_rcp_f32_e32 v169, v169
	v_pk_mul_f32 v[162:163], v[160:161], v[162:163] op_sel_hi:[0,1]
	v_pk_mul_f32 v[164:165], v[160:161], v[164:165] op_sel_hi:[0,1]
	v_pk_mul_f32 v[166:167], v[160:161], v[166:167] op_sel_hi:[0,1]
	v_pk_mul_f32 v[168:169], v[160:161], v[168:169] op_sel_hi:[0,1]
	v_pk_mul_f32 v[72:73], v[72:73], v[162:163]
	v_pk_mul_f32 v[74:75], v[74:75], v[164:165]
	v_pk_mul_f32 v[64:65], v[64:65], v[166:167]
	v_pk_mul_f32 v[66:67], v[66:67], v[168:169]
	v_cvt_pk_bf16_f32 v232, v72, v73
	v_cvt_pk_bf16_f32 v233, v74, v75
	v_cvt_pk_bf16_f32 v234, v64, v65
	v_cvt_pk_bf16_f32 v235, v66, v67
	v_mul_f32_e32 v158, 0xbfb8aa3b, v204
	v_mul_f32_e32 v160, v204, v204
	v_pk_mul_f32 v[162:163], v[60:61], v[158:159] op_sel_hi:[1,0]
	v_pk_mul_f32 v[164:165], v[62:63], v[158:159] op_sel_hi:[1,0]
	v_pk_mul_f32 v[166:167], v[52:53], v[158:159] op_sel_hi:[1,0]
	v_pk_mul_f32 v[168:169], v[54:55], v[158:159] op_sel_hi:[1,0]
	v_exp_f32_e32 v162, v162
	v_exp_f32_e32 v163, v163
	v_pk_mul_f32 v[56:57], v[60:61], v[56:57]
	v_exp_f32_e32 v164, v164
	v_exp_f32_e32 v165, v165
	v_pk_mul_f32 v[58:59], v[62:63], v[58:59]
	v_exp_f32_e32 v166, v166
	v_exp_f32_e32 v167, v167
	v_pk_mul_f32 v[48:49], v[52:53], v[48:49]
	v_exp_f32_e32 v168, v168
	v_exp_f32_e32 v169, v169
	v_pk_mul_f32 v[50:51], v[54:55], v[50:51]
	v_pk_add_f32 v[162:163], v[162:163], v[198:199] op_sel_hi:[1,0]
	v_pk_add_f32 v[164:165], v[164:165], v[198:199] op_sel_hi:[1,0]
	v_pk_add_f32 v[166:167], v[166:167], v[198:199] op_sel_hi:[1,0]
	v_pk_add_f32 v[168:169], v[168:169], v[198:199] op_sel_hi:[1,0]
	v_rcp_f32_e32 v162, v162
	v_rcp_f32_e32 v163, v163
	v_rcp_f32_e32 v164, v164
	v_rcp_f32_e32 v165, v165
	v_rcp_f32_e32 v166, v166
	v_rcp_f32_e32 v167, v167
	v_rcp_f32_e32 v168, v168
	v_rcp_f32_e32 v169, v169
	v_pk_mul_f32 v[162:163], v[160:161], v[162:163] op_sel_hi:[0,1]
	v_pk_mul_f32 v[164:165], v[160:161], v[164:165] op_sel_hi:[0,1]
	v_pk_mul_f32 v[166:167], v[160:161], v[166:167] op_sel_hi:[0,1]
	v_pk_mul_f32 v[168:169], v[160:161], v[168:169] op_sel_hi:[0,1]
	v_pk_mul_f32 v[56:57], v[56:57], v[162:163]
	v_pk_mul_f32 v[58:59], v[58:59], v[164:165]
	v_pk_mul_f32 v[48:49], v[48:49], v[166:167]
	v_pk_mul_f32 v[50:51], v[50:51], v[168:169]
	v_cvt_pk_bf16_f32 v236, v56, v57
	v_cvt_pk_bf16_f32 v237, v58, v59
	v_cvt_pk_bf16_f32 v238, v48, v49
	v_cvt_pk_bf16_f32 v239, v50, v51
	v_mul_f32_e32 v158, 0xbfb8aa3b, v205
	v_mul_f32_e32 v160, v205, v205
	v_pk_mul_f32 v[162:163], v[44:45], v[158:159] op_sel_hi:[1,0]
	v_pk_mul_f32 v[164:165], v[46:47], v[158:159] op_sel_hi:[1,0]
	v_pk_mul_f32 v[166:167], v[36:37], v[158:159] op_sel_hi:[1,0]
	v_pk_mul_f32 v[168:169], v[38:39], v[158:159] op_sel_hi:[1,0]
	v_exp_f32_e32 v162, v162
	v_exp_f32_e32 v163, v163
	v_pk_mul_f32 v[40:41], v[44:45], v[40:41]
	v_exp_f32_e32 v164, v164
	v_exp_f32_e32 v165, v165
	v_pk_mul_f32 v[42:43], v[46:47], v[42:43]
	v_exp_f32_e32 v166, v166
	v_exp_f32_e32 v167, v167
	v_pk_mul_f32 v[32:33], v[36:37], v[32:33]
	v_exp_f32_e32 v168, v168
	v_exp_f32_e32 v169, v169
	v_pk_mul_f32 v[34:35], v[38:39], v[34:35]
	v_pk_add_f32 v[162:163], v[162:163], v[198:199] op_sel_hi:[1,0]
	v_pk_add_f32 v[164:165], v[164:165], v[198:199] op_sel_hi:[1,0]
	v_pk_add_f32 v[166:167], v[166:167], v[198:199] op_sel_hi:[1,0]
	v_pk_add_f32 v[168:169], v[168:169], v[198:199] op_sel_hi:[1,0]
; __device__ __forceinline__ unsigned cvt_pk_bf16(float lo, float hi) { unsigned r; asm volatile("v_cvt_pk_bf16_f32 %0, %1, %2" : "=v"(r) : "v"(lo), "v"(hi)); return r; }
; #define PG8_BAR __builtin_amdgcn_s_barrier()
;     __device__ __forceinline__ void operator()(Acc& acc, const Unit& u, int wr, int wc, int fr, int fq) const {
;     ...
;                     const f32x4 g = acc[ai][0][m][n], up = acc[ai][1][m][n];
;                     const f32x4 t = g * c1; f32x4 e;
; #pragma unroll
;                     for (int i = 0; i < 4; ++i) e[i] = __builtin_amdgcn_exp2f(t[i]);
;                     const f32x4 d = e + 1.0f; f32x4 q;
; #pragma unroll
;                     for (int i = 0; i < 4; ++i) q[i] = __builtin_amdgcn_rcpf(d[i]);
;                     o[n] = (g * up) * (q * r2);
;                 }
;                 u32x4 w; w.x = cvt_pk_bf16(o[0][0], o[0][1]); w.y = cvt_pk_bf16(o[0][2], o[0][3]); w.z = cvt_pk_bf16(o[1][0], o[1][1]); w.w = cvt_pk_bf16(o[1][2], o[1][3]);
;                 *(u32x4*)(O + (size_t)row * DFF + col0) = w;
; template <class Epi, class Sched, bool ALIGN_EPI>
; __device__ __forceinline__ void gemm_phase(LAS unsigned char* lds, const Gemm g, const Sched& S, const Epi& E) {
;     ...
;         E(acc, cur, wr, wc, fr, fq);
;         if (!has_next) break;
; #pragma unroll
;         for (int a = 0; a < 2; ++a)
; #pragma unroll
;             for (int b = 0; b < 2; ++b)
; #pragma unroll
;                 for (int m = 0; m < 4; ++m)
; #pragma unroll
;                     for (int n = 0; n < 2; ++n) acc[a][b][m][n] = (f32x4){0.f, 0.f, 0.f, 0.f};
;         cur = nxt; cA = nA; cB = nB; ++ui;
;         if constexpr (ALIGN_EPI) { if (wr == 1) PG8_BAR; }
	v_rcp_f32_e32 v162, v162
	v_rcp_f32_e32 v163, v163
	v_rcp_f32_e32 v164, v164
	v_rcp_f32_e32 v165, v165
	v_rcp_f32_e32 v166, v166
	v_rcp_f32_e32 v167, v167
	v_rcp_f32_e32 v168, v168
	v_rcp_f32_e32 v169, v169
	v_pk_mul_f32 v[162:163], v[160:161], v[162:163] op_sel_hi:[0,1]
	v_pk_mul_f32 v[164:165], v[160:161], v[164:165] op_sel_hi:[0,1]
	v_pk_mul_f32 v[166:167], v[160:161], v[166:167] op_sel_hi:[0,1]
	v_pk_mul_f32 v[168:169], v[160:161], v[168:169] op_sel_hi:[0,1]
	v_pk_mul_f32 v[40:41], v[40:41], v[162:163]
	v_pk_mul_f32 v[42:43], v[42:43], v[164:165]
	v_pk_mul_f32 v[32:33], v[32:33], v[166:167]
	v_pk_mul_f32 v[34:35], v[34:35], v[168:169]
	v_cvt_pk_bf16_f32 v240, v40, v41
	v_cvt_pk_bf16_f32 v241, v42, v43
	v_cvt_pk_bf16_f32 v242, v32, v33
	v_cvt_pk_bf16_f32 v243, v34, v35
	v_mul_f32_e32 v158, 0xbfb8aa3b, v206
	v_mul_f32_e32 v160, v206, v206
	v_pk_mul_f32 v[162:163], v[28:29], v[158:159] op_sel_hi:[1,0]
	v_pk_mul_f32 v[164:165], v[30:31], v[158:159] op_sel_hi:[1,0]
	v_pk_mul_f32 v[166:167], v[20:21], v[158:159] op_sel_hi:[1,0]
	v_pk_mul_f32 v[168:169], v[22:23], v[158:159] op_sel_hi:[1,0]
	v_exp_f32_e32 v162, v162
	v_exp_f32_e32 v163, v163
	v_pk_mul_f32 v[24:25], v[28:29], v[24:25]
	v_exp_f32_e32 v164, v164
	v_exp_f32_e32 v165, v165
	v_pk_mul_f32 v[26:27], v[30:31], v[26:27]
	v_exp_f32_e32 v166, v166
	v_exp_f32_e32 v167, v167
	v_pk_mul_f32 v[16:17], v[20:21], v[16:17]
	v_exp_f32_e32 v168, v168
	v_exp_f32_e32 v169, v169
	v_pk_mul_f32 v[18:19], v[22:23], v[18:19]
	v_pk_add_f32 v[162:163], v[162:163], v[198:199] op_sel_hi:[1,0]
	v_pk_add_f32 v[164:165], v[164:165], v[198:199] op_sel_hi:[1,0]
	v_pk_add_f32 v[166:167], v[166:167], v[198:199] op_sel_hi:[1,0]
	v_pk_add_f32 v[168:169], v[168:169], v[198:199] op_sel_hi:[1,0]
	v_rcp_f32_e32 v162, v162
	v_rcp_f32_e32 v163, v163
	v_rcp_f32_e32 v164, v164
	v_rcp_f32_e32 v165, v165
	v_rcp_f32_e32 v166, v166
	v_rcp_f32_e32 v167, v167
	v_rcp_f32_e32 v168, v168
	v_rcp_f32_e32 v169, v169
	v_pk_mul_f32 v[162:163], v[160:161], v[162:163] op_sel_hi:[0,1]
	v_pk_mul_f32 v[164:165], v[160:161], v[164:165] op_sel_hi:[0,1]
	v_pk_mul_f32 v[166:167], v[160:161], v[166:167] op_sel_hi:[0,1]
	v_pk_mul_f32 v[168:169], v[160:161], v[168:169] op_sel_hi:[0,1]
	v_pk_mul_f32 v[24:25], v[24:25], v[162:163]
	v_pk_mul_f32 v[26:27], v[26:27], v[164:165]
	v_pk_mul_f32 v[16:17], v[16:17], v[166:167]
	v_pk_mul_f32 v[18:19], v[18:19], v[168:169]
	v_cvt_pk_bf16_f32 v246, v24, v25
	v_cvt_pk_bf16_f32 v247, v26, v27
	v_cvt_pk_bf16_f32 v248, v16, v17
	v_cvt_pk_bf16_f32 v249, v18, v19
	v_mul_f32_e32 v158, 0xbfb8aa3b, v207
	v_mul_f32_e32 v160, v207, v207
	v_pk_mul_f32 v[162:163], v[12:13], v[158:159] op_sel_hi:[1,0]
	v_pk_mul_f32 v[164:165], v[14:15], v[158:159] op_sel_hi:[1,0]
	v_pk_mul_f32 v[166:167], v[4:5], v[158:159] op_sel_hi:[1,0]
	v_pk_mul_f32 v[168:169], v[6:7], v[158:159] op_sel_hi:[1,0]
	v_exp_f32_e32 v162, v162
	v_exp_f32_e32 v163, v163
	v_pk_mul_f32 v[8:9], v[12:13], v[8:9]
	v_exp_f32_e32 v164, v164
	v_exp_f32_e32 v165, v165
	v_pk_mul_f32 v[10:11], v[14:15], v[10:11]
	v_exp_f32_e32 v166, v166
	v_exp_f32_e32 v167, v167
	v_pk_mul_f32 v[0:1], v[4:5], v[0:1]
	v_exp_f32_e32 v168, v168
	v_exp_f32_e32 v169, v169
	v_pk_mul_f32 v[2:3], v[6:7], v[2:3]
	v_pk_add_f32 v[162:163], v[162:163], v[198:199] op_sel_hi:[1,0]
	v_pk_add_f32 v[164:165], v[164:165], v[198:199] op_sel_hi:[1,0]
	v_pk_add_f32 v[166:167], v[166:167], v[198:199] op_sel_hi:[1,0]
	v_pk_add_f32 v[168:169], v[168:169], v[198:199] op_sel_hi:[1,0]
	v_rcp_f32_e32 v162, v162
	v_rcp_f32_e32 v163, v163
	v_rcp_f32_e32 v164, v164
	v_rcp_f32_e32 v165, v165
	v_rcp_f32_e32 v166, v166
	v_rcp_f32_e32 v167, v167
	v_rcp_f32_e32 v168, v168
	v_rcp_f32_e32 v169, v169
	v_pk_mul_f32 v[162:163], v[160:161], v[162:163] op_sel_hi:[0,1]
	v_pk_mul_f32 v[164:165], v[160:161], v[164:165] op_sel_hi:[0,1]
	v_pk_mul_f32 v[166:167], v[160:161], v[166:167] op_sel_hi:[0,1]
	v_pk_mul_f32 v[168:169], v[160:161], v[168:169] op_sel_hi:[0,1]
	v_pk_mul_f32 v[8:9], v[8:9], v[162:163]
	v_pk_mul_f32 v[10:11], v[10:11], v[164:165]
	v_pk_mul_f32 v[0:1], v[0:1], v[166:167]
	v_pk_mul_f32 v[2:3], v[2:3], v[168:169]
	v_cvt_pk_bf16_f32 v250, v8, v9
	v_cvt_pk_bf16_f32 v251, v10, v11
	v_cvt_pk_bf16_f32 v252, v0, v1
	v_cvt_pk_bf16_f32 v253, v2, v3
	v_mov_b32_e32 v254, v155
	s_andn2_b64 vcc, exec, s[2:3]
	s_mov_b64 s[2:3], -1
	s_mov_b32 s101, 1
	s_cbranch_vccz .Lswg_def_1613
	v_add_u32_e32 v255, 0x2c000, v254
	global_store_dwordx4 v255, v[228:231], s[64:65]
	v_add_u32_e32 v244, 0x42000, v254
	global_store_dwordx4 v244, v[232:235], s[64:65]
	v_add_u32_e32 v255, 0xb0000, v254
	global_store_dwordx4 v255, v[236:239], s[64:65]
	v_add_u32_e32 v244, 0xc6000, v254
	global_store_dwordx4 v244, v[240:243], s[64:65]
	v_add_u32_e32 v255, 0xdc000, v254
	global_store_dwordx4 v255, v[246:249], s[64:65]
	v_add_u32_e32 v244, 0xf2000, v254
	global_store_dwordx4 v244, v[250:253], s[64:65]
	s_branch .LBB0_1609
.Lswg_def_1613:
	s_andn2_b64 vcc, exec, s[4:5]
	s_cbranch_vccnz .LBB0_1608
	s_barrier
	s_branch .LBB0_1608
